# EpiRes epilogues (out-proj and FFN-down phases): the 16 residual loads of a unit issued together at the epilogue head into dead fragment registers, one wait; per-block waits that also drained the prev
# speedup vs baseline: 1.0283x; 1.0014x over previous
; __device__ __forceinline__ u32x4 pack8(f32x4 a, f32x4 b) { u32x4 w; w.x = cvt_pk_bf16(a[0], a[1]); w.y = cvt_pk_bf16(a[2], a[3]); w.z = cvt_pk_bf16(b[0], b[1]); w.w = cvt_pk_bf16(b[2], b[3]); return w; }
;     __device__ __forceinline__ void operator()(const AccT& acc, const pg8::Unit& u, int wr, int wc, int fr, int fq) const {
;     ...
;         for (int ai = 0; ai < 2; ++ai)
; #pragma unroll
;             for (int m = 0; m < 4; ++m) {
;                 const int row = u.pm * 256 + ai * 128 + wr * 64 + m * 16 + fr;
;                 const size_t off = (size_t)row * 1024 + u.pn * 256 + 32 * wc + 8 * fq;
;                 float ss = 0.f;
; #pragma unroll
;                 for (int bj = 0; bj < 2; ++bj) {
;                     const u32x4 bv = *(const u32x4*)(XB + off + 128 * bj);
;                     f32x4 b0, b1;
;                     b0[0] = __builtin_bit_cast(float, bv[0] << 16); b0[1] = __builtin_bit_cast(float, bv[0] & 0xffff0000u); b0[2] = __builtin_bit_cast(float, bv[1] << 16); b0[3] = __builtin_bit_cast(float, bv[1] & 0xffff0000u);
;                     b1[0] = __builtin_bit_cast(float, bv[2] << 16); b1[1] = __builtin_bit_cast(float, bv[2] & 0xffff0000u); b1[2] = __builtin_bit_cast(float, bv[3] << 16); b1[3] = __builtin_bit_cast(float, bv[3] & 0xffff0000u);
;                     const f32x4 o0 = b0 + acc[ai][bj][m][0], o1 = b1 + acc[ai][bj][m][1];
;                     if (LAST) { *(f32x4*)(out + off + 128 * bj) = o0; *(f32x4*)(out + off + 128 * bj + 4) = o1; }
;                     else {
;                         *(u32x4*)(XB + off + 128 * bj) = pack8(o0, o1);
;                         ss += ((o0[0] * o0[0] + o0[1] * o0[1]) + (o0[2] * o0[2] + o0[3] * o0[3])) + ((o1[0] * o1[0] + o1[1] * o1[1]) + (o1[2] * o1[2] + o1[3] * o1[3]));
;                     }
;                 }
;                 if (!LAST) {
;                     ss += __shfl_xor(ss, 16); ss += __shfl_xor(ss, 32);
;                     if (fq == 0) ssq_out[(size_t)row * 16 + u.pn * 4 + wc] = ss;
;                 }
.LBB0_502:
	s_mov_b32 s21, s50
	v_mov_b32_e32 v136, v220
	s_mov_b32 s34, s57
	s_lshl_b32 s23, s30, 8
	s_lshl_b32 s21, s21, 6
	s_add_i32 s21, s21, s23
	v_and_or_b32 v146, v136, 15, s21
	v_ashrrev_i32_e32 v147, 31, v146
	s_lshl_b32 s30, s28, 8
	v_lshlrev_b64 v[156:157], 11, v[146:147]
	s_ashr_i32 s31, s30, 31
	s_lshl_b32 s36, s34, 5
	v_lshl_add_u64 v[156:157], s[12:13], 0, v[156:157]
	v_bfe_u32 v155, v136, 4, 2
	s_ashr_i32 s37, s36, 31
	v_lshl_add_u64 v[156:157], s[30:31], 1, v[156:157]
	v_lshl_add_u64 v[156:157], s[36:37], 1, v[156:157]
	v_lshlrev_b32_e32 v136, 4, v155
	v_lshl_add_u64 v[164:165], v[156:157], 0, v[136:137]
	s_mov_b32 s88, 0x8000
	s_mov_b32 s89, 0
	s_mov_b32 s90, 0x28000
	s_mov_b32 s91, 0
	global_load_dwordx4 v[174:177], v[164:165], off
	global_load_dwordx4 v[178:181], v[164:165], off offset:256
	v_lshl_add_u64 v[244:245], v[164:165], 0, s[88:89]
	global_load_dwordx4 v[182:185], v[244:245], off
	global_load_dwordx4 v[186:189], v[244:245], off offset:256
	v_lshl_add_u64 v[244:245], v[244:245], 0, s[88:89]
	global_load_dwordx4 v[190:193], v[244:245], off
	global_load_dwordx4 v[194:197], v[244:245], off offset:256
	v_lshl_add_u64 v[244:245], v[244:245], 0, s[88:89]
	global_load_dwordx4 v[198:201], v[244:245], off
	global_load_dwordx4 v[202:205], v[244:245], off offset:256
	v_lshl_add_u64 v[244:245], v[244:245], 0, s[90:91]
	global_load_dwordx4 v[206:209], v[244:245], off
	global_load_dwordx4 v[210:213], v[244:245], off offset:256
	v_lshl_add_u64 v[244:245], v[244:245], 0, s[88:89]
	global_load_dwordx4 v[214:217], v[244:245], off
	global_load_dwordx4 v[224:227], v[244:245], off offset:256
	v_lshl_add_u64 v[244:245], v[244:245], 0, s[88:89]
	global_load_dwordx4 v[228:231], v[244:245], off
	global_load_dwordx4 v[232:235], v[244:245], off offset:256
	v_lshl_add_u64 v[244:245], v[244:245], 0, s[88:89]
	global_load_dwordx4 v[236:239], v[244:245], off
	global_load_dwordx4 v[240:243], v[244:245], off offset:256
	s_waitcnt vmcnt(0)
	s_nop 1
	v_mov_b32_e32 v156, v174
	v_mov_b32_e32 v157, v175
	v_mov_b32_e32 v158, v176
	v_mov_b32_e32 v159, v177
	s_nop 1
	v_mov_b32_e32 v160, v178
	v_mov_b32_e32 v161, v179
	v_mov_b32_e32 v162, v180
	v_mov_b32_e32 v163, v181
	v_and_b32_e32 v153, 64, v152
	v_xor_b32_e32 v136, 16, v152
	v_add_u32_e32 v153, 64, v153
	v_xor_b32_e32 v154, 32, v152
	v_cmp_lt_i32_e32 vcc, v136, v153
	s_lshl_b32 s28, s28, 2
	s_ashr_i32 s29, s28, 31
	v_cndmask_b32_e32 v136, v152, v136, vcc
	v_cmp_lt_i32_e32 vcc, v154, v153
	s_ashr_i32 s35, s34, 31
	v_lshlrev_b32_e32 v166, 16, v156
	v_and_b32_e32 v167, 0xffff0000, v156
	v_lshlrev_b32_e32 v156, 16, v157
	v_and_b32_e32 v157, 0xffff0000, v157
	v_lshlrev_b32_e32 v168, 16, v158
	v_and_b32_e32 v169, 0xffff0000, v158
	v_lshlrev_b32_e32 v158, 16, v159
	v_and_b32_e32 v159, 0xffff0000, v159
	v_lshlrev_b32_e32 v170, 16, v160
	v_and_b32_e32 v171, 0xffff0000, v160
	v_lshlrev_b32_e32 v160, 16, v161
	v_and_b32_e32 v161, 0xffff0000, v161
	v_lshlrev_b32_e32 v172, 16, v162
	v_and_b32_e32 v173, 0xffff0000, v162
	v_lshlrev_b32_e32 v162, 16, v163
	v_and_b32_e32 v163, 0xffff0000, v163
	v_pk_add_f32 v[126:127], v[126:127], v[156:157]
	v_pk_add_f32 v[124:125], v[124:125], v[166:167]
	v_pk_add_f32 v[122:123], v[122:123], v[158:159]
	v_pk_add_f32 v[120:121], v[120:121], v[168:169]
	v_pk_add_f32 v[118:119], v[118:119], v[160:161]
	v_pk_add_f32 v[116:117], v[116:117], v[170:171]
	v_pk_add_f32 v[156:157], v[114:115], v[162:163]
	v_pk_add_f32 v[158:159], v[112:113], v[172:173]
	v_cndmask_b32_e32 v153, v152, v154, vcc
	v_lshlrev_b32_e32 v154, 2, v136
	v_cvt_pk_bf16_f32 v112, v124, v125
	v_cvt_pk_bf16_f32 v113, v126, v127
	v_mul_f32_e32 v114, v125, v125
	v_mul_f32_e32 v115, v127, v127
	v_mul_f32_e32 v125, v121, v121
	v_mul_f32_e32 v127, v123, v123
	v_mul_f32_e32 v136, v117, v117
	v_mul_f32_e32 v160, v119, v119
	v_mul_f32_e32 v161, v159, v159
	v_mul_f32_e32 v162, v157, v157
	v_fmac_f32_e32 v114, v124, v124
	v_fmac_f32_e32 v115, v126, v126
	v_fmac_f32_e32 v125, v120, v120
	v_fmac_f32_e32 v127, v122, v122
	v_fmac_f32_e32 v136, v116, v116
	v_fmac_f32_e32 v160, v118, v118
	v_fmac_f32_e32 v161, v158, v158
	v_fmac_f32_e32 v162, v156, v156
	v_add_f32_e32 v114, v114, v115
	v_add_f32_e32 v115, v125, v127
	v_add_f32_e32 v124, v136, v160
	v_add_f32_e32 v125, v161, v162
	v_add_f32_e32 v114, v114, v115
	v_add_f32_e32 v115, v124, v125
	v_add_f32_e32 v124, v114, v115
	ds_bpermute_b32 v125, v154, v124
	v_cvt_pk_bf16_f32 v114, v120, v121
	v_cvt_pk_bf16_f32 v115, v122, v123
	v_lshlrev_b32_e32 v153, 2, v153
	global_store_dwordx4 v[164:165], v[112:115], off
	v_cmp_eq_u32_e32 vcc, 0, v155
	s_waitcnt lgkmcnt(0)
	v_add_f32_e32 v112, v124, v125
	ds_bpermute_b32 v113, v153, v112
	v_cvt_pk_bf16_f32 v114, v116, v117
	v_cvt_pk_bf16_f32 v115, v118, v119
	v_cvt_pk_bf16_f32 v116, v158, v159
	v_cvt_pk_bf16_f32 v117, v156, v157
	global_store_dwordx4 v[164:165], v[114:117], off offset:256
	s_and_saveexec_b64 s[38:39], vcc
	s_cbranch_execz .LBB0_504
	s_waitcnt lgkmcnt(0)
	v_add_f32_e32 v114, v112, v113
	v_lshlrev_b64 v[112:113], 6, v[146:147]
	v_lshl_add_u64 v[112:113], s[14:15], 0, v[112:113]
	v_lshl_add_u64 v[112:113], s[28:29], 2, v[112:113]
	v_lshl_add_u64 v[112:113], s[34:35], 2, v[112:113]
	global_store_dword v[112:113], v114, off
; __device__ __forceinline__ u32x4 pack8(f32x4 a, f32x4 b) { u32x4 w; w.x = cvt_pk_bf16(a[0], a[1]); w.y = cvt_pk_bf16(a[2], a[3]); w.z = cvt_pk_bf16(b[0], b[1]); w.w = cvt_pk_bf16(b[2], b[3]); return w; }
;     __device__ __forceinline__ void operator()(const AccT& acc, const pg8::Unit& u, int wr, int wc, int fr, int fq) const {
;     ...
;         for (int ai = 0; ai < 2; ++ai)
; #pragma unroll
;             for (int m = 0; m < 4; ++m) {
;                 const int row = u.pm * 256 + ai * 128 + wr * 64 + m * 16 + fr;
;                 const size_t off = (size_t)row * 1024 + u.pn * 256 + 32 * wc + 8 * fq;
;                 float ss = 0.f;
; #pragma unroll
;                 for (int bj = 0; bj < 2; ++bj) {
;                     const u32x4 bv = *(const u32x4*)(XB + off + 128 * bj);
;                     f32x4 b0, b1;
;                     b0[0] = __builtin_bit_cast(float, bv[0] << 16); b0[1] = __builtin_bit_cast(float, bv[0] & 0xffff0000u); b0[2] = __builtin_bit_cast(float, bv[1] << 16); b0[3] = __builtin_bit_cast(float, bv[1] & 0xffff0000u);
;                     b1[0] = __builtin_bit_cast(float, bv[2] << 16); b1[1] = __builtin_bit_cast(float, bv[2] & 0xffff0000u); b1[2] = __builtin_bit_cast(float, bv[3] << 16); b1[3] = __builtin_bit_cast(float, bv[3] & 0xffff0000u);
;                     const f32x4 o0 = b0 + acc[ai][bj][m][0], o1 = b1 + acc[ai][bj][m][1];
;                     if (LAST) { *(f32x4*)(out + off + 128 * bj) = o0; *(f32x4*)(out + off + 128 * bj + 4) = o1; }
;                     else {
;                         *(u32x4*)(XB + off + 128 * bj) = pack8(o0, o1);
;                         ss += ((o0[0] * o0[0] + o0[1] * o0[1]) + (o0[2] * o0[2] + o0[3] * o0[3])) + ((o1[0] * o1[0] + o1[1] * o1[1]) + (o1[2] * o1[2] + o1[3] * o1[3]));
;                     }
;                 }
;                 if (!LAST) {
;                     ss += __shfl_xor(ss, 16); ss += __shfl_xor(ss, 32);
;                     if (fq == 0) ssq_out[(size_t)row * 16 + u.pn * 4 + wc] = ss;
;                 }
.LBB0_504:
	s_or_b64 exec, exec, s[38:39]
	v_or_b32_e32 v112, 16, v146
	s_waitcnt lgkmcnt(0)
	v_ashrrev_i32_e32 v113, 31, v112
	v_lshlrev_b64 v[114:115], 11, v[112:113]
	v_lshl_add_u64 v[114:115], s[12:13], 0, v[114:115]
	v_lshlrev_b32_e32 v116, 3, v155
	v_lshl_add_u64 v[114:115], s[30:31], 1, v[114:115]
	v_lshl_add_u64 v[114:115], s[36:37], 1, v[114:115]
	v_lshlrev_b32_e32 v136, 1, v116
	v_lshl_add_u64 v[122:123], v[114:115], 0, v[136:137]
	s_nop 1
	v_mov_b32_e32 v114, v182
	v_mov_b32_e32 v115, v183
	v_mov_b32_e32 v116, v184
	v_mov_b32_e32 v117, v185
	s_nop 1
	v_mov_b32_e32 v118, v186
	v_mov_b32_e32 v119, v187
	v_mov_b32_e32 v120, v188
	v_mov_b32_e32 v121, v189
	v_lshlrev_b32_e32 v124, 16, v114
	v_and_b32_e32 v125, 0xffff0000, v114
	v_lshlrev_b32_e32 v114, 16, v115
	v_and_b32_e32 v115, 0xffff0000, v115
	v_lshlrev_b32_e32 v126, 16, v116
	v_and_b32_e32 v127, 0xffff0000, v116
	v_lshlrev_b32_e32 v116, 16, v117
	v_and_b32_e32 v117, 0xffff0000, v117
	v_lshlrev_b32_e32 v156, 16, v118
	v_and_b32_e32 v157, 0xffff0000, v118
	v_lshlrev_b32_e32 v118, 16, v119
	v_and_b32_e32 v119, 0xffff0000, v119
	v_lshlrev_b32_e32 v158, 16, v120
	v_and_b32_e32 v159, 0xffff0000, v120
	v_lshlrev_b32_e32 v120, 16, v121
	v_and_b32_e32 v121, 0xffff0000, v121
	v_pk_add_f32 v[110:111], v[110:111], v[114:115]
	v_pk_add_f32 v[108:109], v[108:109], v[124:125]
	v_pk_add_f32 v[106:107], v[106:107], v[116:117]
	v_pk_add_f32 v[104:105], v[104:105], v[126:127]
	v_pk_add_f32 v[102:103], v[102:103], v[118:119]
	v_pk_add_f32 v[100:101], v[100:101], v[156:157]
	v_pk_add_f32 v[114:115], v[98:99], v[120:121]
	v_pk_add_f32 v[116:117], v[96:97], v[158:159]
	v_cvt_pk_bf16_f32 v96, v108, v109
	v_cvt_pk_bf16_f32 v97, v110, v111
	v_mul_f32_e32 v98, v109, v109
	v_mul_f32_e32 v99, v111, v111
	v_mul_f32_e32 v109, v105, v105
	v_mul_f32_e32 v111, v107, v107
	v_mul_f32_e32 v118, v101, v101
	v_mul_f32_e32 v119, v103, v103
	v_mul_f32_e32 v120, v117, v117
	v_mul_f32_e32 v121, v115, v115
	v_fmac_f32_e32 v98, v108, v108
	v_fmac_f32_e32 v99, v110, v110
	v_fmac_f32_e32 v109, v104, v104
	v_fmac_f32_e32 v111, v106, v106
	v_fmac_f32_e32 v118, v100, v100
	v_fmac_f32_e32 v119, v102, v102
	v_fmac_f32_e32 v120, v116, v116
	v_fmac_f32_e32 v121, v114, v114
	v_add_f32_e32 v98, v98, v99
	v_add_f32_e32 v99, v109, v111
	v_add_f32_e32 v108, v118, v119
	v_add_f32_e32 v109, v120, v121
	v_add_f32_e32 v98, v98, v99
	v_add_f32_e32 v99, v108, v109
	v_add_f32_e32 v108, v98, v99
	ds_bpermute_b32 v109, v154, v108
	v_cvt_pk_bf16_f32 v98, v104, v105
	v_cvt_pk_bf16_f32 v99, v106, v107
	global_store_dwordx4 v[122:123], v[96:99], off
	s_waitcnt lgkmcnt(0)
	s_nop 0
	v_add_f32_e32 v96, v108, v109
	ds_bpermute_b32 v97, v153, v96
	v_cvt_pk_bf16_f32 v98, v100, v101
	v_cvt_pk_bf16_f32 v99, v102, v103
	v_cvt_pk_bf16_f32 v100, v116, v117
	v_cvt_pk_bf16_f32 v101, v114, v115
	global_store_dwordx4 v[122:123], v[98:101], off offset:256
	s_and_saveexec_b64 s[38:39], vcc
	s_cbranch_execz .LBB0_506
	s_waitcnt lgkmcnt(0)
	v_add_f32_e32 v98, v96, v97
	v_lshlrev_b64 v[96:97], 6, v[112:113]
	v_lshl_add_u64 v[96:97], s[14:15], 0, v[96:97]
	v_lshl_add_u64 v[96:97], s[28:29], 2, v[96:97]
	v_lshl_add_u64 v[96:97], s[34:35], 2, v[96:97]
	global_store_dword v[96:97], v98, off
.LBB0_506:
	s_or_b64 exec, exec, s[38:39]
	v_or_b32_e32 v96, 32, v146
	s_waitcnt lgkmcnt(0)
	v_ashrrev_i32_e32 v97, 31, v96
	v_lshlrev_b64 v[98:99], 11, v[96:97]
	v_lshl_add_u64 v[98:99], s[12:13], 0, v[98:99]
	v_lshl_add_u64 v[98:99], s[30:31], 1, v[98:99]
	v_lshl_add_u64 v[98:99], s[36:37], 1, v[98:99]
	v_lshl_add_u64 v[106:107], v[98:99], 0, v[136:137]
	s_nop 1
	v_mov_b32_e32 v98, v190
	v_mov_b32_e32 v99, v191
	v_mov_b32_e32 v100, v192
	v_mov_b32_e32 v101, v193
	s_nop 1
	v_mov_b32_e32 v102, v194
	v_mov_b32_e32 v103, v195
	v_mov_b32_e32 v104, v196
	v_mov_b32_e32 v105, v197
	v_lshlrev_b32_e32 v108, 16, v98
	v_and_b32_e32 v109, 0xffff0000, v98
	v_lshlrev_b32_e32 v98, 16, v99
	v_and_b32_e32 v99, 0xffff0000, v99
	v_lshlrev_b32_e32 v110, 16, v100
	v_and_b32_e32 v111, 0xffff0000, v100
	v_lshlrev_b32_e32 v100, 16, v101
	v_and_b32_e32 v101, 0xffff0000, v101
	v_lshlrev_b32_e32 v112, 16, v102
	v_and_b32_e32 v113, 0xffff0000, v102
	v_lshlrev_b32_e32 v102, 16, v103
	v_and_b32_e32 v103, 0xffff0000, v103
	v_lshlrev_b32_e32 v114, 16, v104
	v_and_b32_e32 v115, 0xffff0000, v104
	v_lshlrev_b32_e32 v104, 16, v105
	v_and_b32_e32 v105, 0xffff0000, v105
	v_pk_add_f32 v[94:95], v[94:95], v[98:99]
	v_pk_add_f32 v[92:93], v[92:93], v[108:109]
	v_pk_add_f32 v[90:91], v[90:91], v[100:101]
	v_pk_add_f32 v[88:89], v[88:89], v[110:111]
	v_pk_add_f32 v[86:87], v[86:87], v[102:103]
	v_pk_add_f32 v[84:85], v[84:85], v[112:113]
	v_pk_add_f32 v[98:99], v[82:83], v[104:105]
	v_pk_add_f32 v[100:101], v[80:81], v[114:115]
	v_cvt_pk_bf16_f32 v80, v92, v93
	v_cvt_pk_bf16_f32 v81, v94, v95
	v_mul_f32_e32 v82, v93, v93
	v_mul_f32_e32 v83, v95, v95
	v_mul_f32_e32 v93, v89, v89
	v_mul_f32_e32 v95, v91, v91
	v_mul_f32_e32 v102, v85, v85
	v_mul_f32_e32 v103, v87, v87
	v_mul_f32_e32 v104, v101, v101
	v_mul_f32_e32 v105, v99, v99
	v_fmac_f32_e32 v82, v92, v92
	v_fmac_f32_e32 v83, v94, v94
	v_fmac_f32_e32 v93, v88, v88
	v_fmac_f32_e32 v95, v90, v90
	v_fmac_f32_e32 v102, v84, v84
	v_fmac_f32_e32 v103, v86, v86
	v_fmac_f32_e32 v104, v100, v100
	v_fmac_f32_e32 v105, v98, v98
	v_add_f32_e32 v82, v82, v83
	v_add_f32_e32 v83, v93, v95
	v_add_f32_e32 v92, v102, v103
	v_add_f32_e32 v93, v104, v105
	v_add_f32_e32 v82, v82, v83
	v_add_f32_e32 v83, v92, v93
	v_add_f32_e32 v92, v82, v83
	ds_bpermute_b32 v93, v154, v92
	v_cvt_pk_bf16_f32 v82, v88, v89
	v_cvt_pk_bf16_f32 v83, v90, v91
	global_store_dwordx4 v[106:107], v[80:83], off
	s_waitcnt lgkmcnt(0)
	s_nop 0
	v_add_f32_e32 v80, v92, v93
	ds_bpermute_b32 v81, v153, v80
	v_cvt_pk_bf16_f32 v82, v84, v85
	v_cvt_pk_bf16_f32 v83, v86, v87
	v_cvt_pk_bf16_f32 v84, v100, v101
	v_cvt_pk_bf16_f32 v85, v98, v99
	global_store_dwordx4 v[106:107], v[82:85], off offset:256
	s_and_saveexec_b64 s[38:39], vcc
	s_cbranch_execz .LBB0_508
	s_waitcnt lgkmcnt(0)
	v_add_f32_e32 v82, v80, v81
	v_lshlrev_b64 v[80:81], 6, v[96:97]
	v_lshl_add_u64 v[80:81], s[14:15], 0, v[80:81]
	v_lshl_add_u64 v[80:81], s[28:29], 2, v[80:81]
	v_lshl_add_u64 v[80:81], s[34:35], 2, v[80:81]
	global_store_dword v[80:81], v82, off
; __device__ __forceinline__ u32x4 pack8(f32x4 a, f32x4 b) { u32x4 w; w.x = cvt_pk_bf16(a[0], a[1]); w.y = cvt_pk_bf16(a[2], a[3]); w.z = cvt_pk_bf16(b[0], b[1]); w.w = cvt_pk_bf16(b[2], b[3]); return w; }
;     __device__ __forceinline__ void operator()(const AccT& acc, const pg8::Unit& u, int wr, int wc, int fr, int fq) const {
;     ...
;         for (int ai = 0; ai < 2; ++ai)
; #pragma unroll
;             for (int m = 0; m < 4; ++m) {
;                 const int row = u.pm * 256 + ai * 128 + wr * 64 + m * 16 + fr;
;                 const size_t off = (size_t)row * 1024 + u.pn * 256 + 32 * wc + 8 * fq;
;                 float ss = 0.f;
; #pragma unroll
;                 for (int bj = 0; bj < 2; ++bj) {
;                     const u32x4 bv = *(const u32x4*)(XB + off + 128 * bj);
;                     f32x4 b0, b1;
;                     b0[0] = __builtin_bit_cast(float, bv[0] << 16); b0[1] = __builtin_bit_cast(float, bv[0] & 0xffff0000u); b0[2] = __builtin_bit_cast(float, bv[1] << 16); b0[3] = __builtin_bit_cast(float, bv[1] & 0xffff0000u);
;                     b1[0] = __builtin_bit_cast(float, bv[2] << 16); b1[1] = __builtin_bit_cast(float, bv[2] & 0xffff0000u); b1[2] = __builtin_bit_cast(float, bv[3] << 16); b1[3] = __builtin_bit_cast(float, bv[3] & 0xffff0000u);
;                     const f32x4 o0 = b0 + acc[ai][bj][m][0], o1 = b1 + acc[ai][bj][m][1];
;                     if (LAST) { *(f32x4*)(out + off + 128 * bj) = o0; *(f32x4*)(out + off + 128 * bj + 4) = o1; }
;                     else {
;                         *(u32x4*)(XB + off + 128 * bj) = pack8(o0, o1);
;                         ss += ((o0[0] * o0[0] + o0[1] * o0[1]) + (o0[2] * o0[2] + o0[3] * o0[3])) + ((o1[0] * o1[0] + o1[1] * o1[1]) + (o1[2] * o1[2] + o1[3] * o1[3]));
;                     }
;                 }
;                 if (!LAST) {
;                     ss += __shfl_xor(ss, 16); ss += __shfl_xor(ss, 32);
;                     if (fq == 0) ssq_out[(size_t)row * 16 + u.pn * 4 + wc] = ss;
;                 }
.LBB0_508:
	s_or_b64 exec, exec, s[38:39]
	v_or_b32_e32 v80, 48, v146
	s_waitcnt lgkmcnt(0)
	v_ashrrev_i32_e32 v81, 31, v80
	v_lshlrev_b64 v[82:83], 11, v[80:81]
	v_lshl_add_u64 v[82:83], s[12:13], 0, v[82:83]
	v_lshl_add_u64 v[82:83], s[30:31], 1, v[82:83]
	v_lshl_add_u64 v[82:83], s[36:37], 1, v[82:83]
	v_lshl_add_u64 v[90:91], v[82:83], 0, v[136:137]
	s_nop 1
	v_mov_b32_e32 v82, v198
	v_mov_b32_e32 v83, v199
	v_mov_b32_e32 v84, v200
	v_mov_b32_e32 v85, v201
	s_nop 1
	v_mov_b32_e32 v86, v202
	v_mov_b32_e32 v87, v203
	v_mov_b32_e32 v88, v204
	v_mov_b32_e32 v89, v205
	v_lshlrev_b32_e32 v92, 16, v82
	v_and_b32_e32 v93, 0xffff0000, v82
	v_lshlrev_b32_e32 v82, 16, v83
	v_and_b32_e32 v83, 0xffff0000, v83
	v_lshlrev_b32_e32 v94, 16, v84
	v_and_b32_e32 v95, 0xffff0000, v84
	v_lshlrev_b32_e32 v84, 16, v85
	v_and_b32_e32 v85, 0xffff0000, v85
	v_lshlrev_b32_e32 v96, 16, v86
	v_and_b32_e32 v97, 0xffff0000, v86
	v_lshlrev_b32_e32 v86, 16, v87
	v_and_b32_e32 v87, 0xffff0000, v87
	v_lshlrev_b32_e32 v98, 16, v88
	v_and_b32_e32 v99, 0xffff0000, v88
	v_lshlrev_b32_e32 v88, 16, v89
	v_and_b32_e32 v89, 0xffff0000, v89
	v_pk_add_f32 v[78:79], v[78:79], v[82:83]
	v_pk_add_f32 v[76:77], v[76:77], v[92:93]
	v_pk_add_f32 v[74:75], v[74:75], v[84:85]
	v_pk_add_f32 v[72:73], v[72:73], v[94:95]
	v_pk_add_f32 v[70:71], v[70:71], v[86:87]
	v_pk_add_f32 v[68:69], v[68:69], v[96:97]
	v_pk_add_f32 v[82:83], v[66:67], v[88:89]
	v_pk_add_f32 v[84:85], v[64:65], v[98:99]
	v_cvt_pk_bf16_f32 v64, v76, v77
	v_cvt_pk_bf16_f32 v65, v78, v79
	v_mul_f32_e32 v66, v77, v77
	v_mul_f32_e32 v67, v79, v79
	v_mul_f32_e32 v77, v73, v73
	v_mul_f32_e32 v79, v75, v75
	v_mul_f32_e32 v86, v69, v69
	v_mul_f32_e32 v87, v71, v71
	v_mul_f32_e32 v88, v85, v85
	v_mul_f32_e32 v89, v83, v83
	v_fmac_f32_e32 v66, v76, v76
	v_fmac_f32_e32 v67, v78, v78
	v_fmac_f32_e32 v77, v72, v72
	v_fmac_f32_e32 v79, v74, v74
	v_fmac_f32_e32 v86, v68, v68
	v_fmac_f32_e32 v87, v70, v70
	v_fmac_f32_e32 v88, v84, v84
	v_fmac_f32_e32 v89, v82, v82
	v_add_f32_e32 v66, v66, v67
	v_add_f32_e32 v67, v77, v79
	v_add_f32_e32 v76, v86, v87
	v_add_f32_e32 v77, v88, v89
	v_add_f32_e32 v66, v66, v67
	v_add_f32_e32 v67, v76, v77
	v_add_f32_e32 v76, v66, v67
	ds_bpermute_b32 v77, v154, v76
	v_cvt_pk_bf16_f32 v66, v72, v73
	v_cvt_pk_bf16_f32 v67, v74, v75
	global_store_dwordx4 v[90:91], v[64:67], off
	s_waitcnt lgkmcnt(0)
	s_nop 0
	v_add_f32_e32 v64, v76, v77
	ds_bpermute_b32 v65, v153, v64
	v_cvt_pk_bf16_f32 v66, v68, v69
	v_cvt_pk_bf16_f32 v67, v70, v71
	v_cvt_pk_bf16_f32 v68, v84, v85
	v_cvt_pk_bf16_f32 v69, v82, v83
	global_store_dwordx4 v[90:91], v[66:69], off offset:256
	s_and_saveexec_b64 s[38:39], vcc
	s_cbranch_execz .LBB0_510
	s_waitcnt lgkmcnt(0)
	v_add_f32_e32 v66, v64, v65
	v_lshlrev_b64 v[64:65], 6, v[80:81]
	v_lshl_add_u64 v[64:65], s[14:15], 0, v[64:65]
	v_lshl_add_u64 v[64:65], s[28:29], 2, v[64:65]
	v_lshl_add_u64 v[64:65], s[34:35], 2, v[64:65]
	global_store_dword v[64:65], v66, off
.LBB0_510:
	s_or_b64 exec, exec, s[38:39]
	v_add_u32_e32 v64, 0x80, v146
	s_waitcnt lgkmcnt(0)
	v_ashrrev_i32_e32 v65, 31, v64
	v_lshlrev_b64 v[66:67], 11, v[64:65]
	v_lshl_add_u64 v[66:67], s[12:13], 0, v[66:67]
	v_lshl_add_u64 v[66:67], s[30:31], 1, v[66:67]
	v_lshl_add_u64 v[66:67], s[36:37], 1, v[66:67]
	v_lshl_add_u64 v[74:75], v[66:67], 0, v[136:137]
	s_nop 1
	v_mov_b32_e32 v66, v206
	v_mov_b32_e32 v67, v207
	v_mov_b32_e32 v68, v208
	v_mov_b32_e32 v69, v209
	s_nop 1
	v_mov_b32_e32 v70, v210
	v_mov_b32_e32 v71, v211
	v_mov_b32_e32 v72, v212
	v_mov_b32_e32 v73, v213
	v_lshlrev_b32_e32 v76, 16, v66
	v_and_b32_e32 v77, 0xffff0000, v66
	v_lshlrev_b32_e32 v66, 16, v67
	v_and_b32_e32 v67, 0xffff0000, v67
	v_lshlrev_b32_e32 v78, 16, v68
	v_and_b32_e32 v79, 0xffff0000, v68
	v_lshlrev_b32_e32 v68, 16, v69
	v_and_b32_e32 v69, 0xffff0000, v69
	v_lshlrev_b32_e32 v80, 16, v70
	v_and_b32_e32 v81, 0xffff0000, v70
	v_lshlrev_b32_e32 v70, 16, v71
	v_and_b32_e32 v71, 0xffff0000, v71
	v_lshlrev_b32_e32 v82, 16, v72
	v_and_b32_e32 v83, 0xffff0000, v72
	v_lshlrev_b32_e32 v72, 16, v73
	v_and_b32_e32 v73, 0xffff0000, v73
	v_pk_add_f32 v[62:63], v[62:63], v[66:67]
	v_pk_add_f32 v[60:61], v[60:61], v[76:77]
	v_pk_add_f32 v[58:59], v[58:59], v[68:69]
	v_pk_add_f32 v[56:57], v[56:57], v[78:79]
	v_pk_add_f32 v[54:55], v[54:55], v[70:71]
	v_pk_add_f32 v[52:53], v[52:53], v[80:81]
	v_pk_add_f32 v[66:67], v[50:51], v[72:73]
	v_pk_add_f32 v[68:69], v[48:49], v[82:83]
	v_cvt_pk_bf16_f32 v48, v60, v61
	v_cvt_pk_bf16_f32 v49, v62, v63
	v_mul_f32_e32 v50, v61, v61
	v_mul_f32_e32 v51, v63, v63
	v_mul_f32_e32 v61, v57, v57
	v_mul_f32_e32 v63, v59, v59
	v_mul_f32_e32 v70, v53, v53
	v_mul_f32_e32 v71, v55, v55
	v_mul_f32_e32 v72, v69, v69
	v_mul_f32_e32 v73, v67, v67
	v_fmac_f32_e32 v50, v60, v60
	v_fmac_f32_e32 v51, v62, v62
	v_fmac_f32_e32 v61, v56, v56
	v_fmac_f32_e32 v63, v58, v58
	v_fmac_f32_e32 v70, v52, v52
	v_fmac_f32_e32 v71, v54, v54
	v_fmac_f32_e32 v72, v68, v68
	v_fmac_f32_e32 v73, v66, v66
	v_add_f32_e32 v50, v50, v51
	v_add_f32_e32 v51, v61, v63
	v_add_f32_e32 v60, v70, v71
	v_add_f32_e32 v61, v72, v73
	v_add_f32_e32 v50, v50, v51
	v_add_f32_e32 v51, v60, v61
	v_add_f32_e32 v60, v50, v51
	ds_bpermute_b32 v61, v154, v60
	v_cvt_pk_bf16_f32 v50, v56, v57
	v_cvt_pk_bf16_f32 v51, v58, v59
	global_store_dwordx4 v[74:75], v[48:51], off
	s_waitcnt lgkmcnt(0)
	s_nop 0
	v_add_f32_e32 v48, v60, v61
	ds_bpermute_b32 v49, v153, v48
	v_cvt_pk_bf16_f32 v50, v52, v53
	v_cvt_pk_bf16_f32 v51, v54, v55
	v_cvt_pk_bf16_f32 v52, v68, v69
	v_cvt_pk_bf16_f32 v53, v66, v67
	global_store_dwordx4 v[74:75], v[50:53], off offset:256
	s_and_saveexec_b64 s[38:39], vcc
	s_cbranch_execz .LBB0_512
	s_waitcnt lgkmcnt(0)
	v_add_f32_e32 v50, v48, v49
	v_lshlrev_b64 v[48:49], 6, v[64:65]
	v_lshl_add_u64 v[48:49], s[14:15], 0, v[48:49]
	v_lshl_add_u64 v[48:49], s[28:29], 2, v[48:49]
	v_lshl_add_u64 v[48:49], s[34:35], 2, v[48:49]
	global_store_dword v[48:49], v50, off
; __device__ __forceinline__ u32x4 pack8(f32x4 a, f32x4 b) { u32x4 w; w.x = cvt_pk_bf16(a[0], a[1]); w.y = cvt_pk_bf16(a[2], a[3]); w.z = cvt_pk_bf16(b[0], b[1]); w.w = cvt_pk_bf16(b[2], b[3]); return w; }
;     __device__ __forceinline__ void operator()(const AccT& acc, const pg8::Unit& u, int wr, int wc, int fr, int fq) const {
;     ...
;         for (int ai = 0; ai < 2; ++ai)
; #pragma unroll
;             for (int m = 0; m < 4; ++m) {
;                 const int row = u.pm * 256 + ai * 128 + wr * 64 + m * 16 + fr;
;                 const size_t off = (size_t)row * 1024 + u.pn * 256 + 32 * wc + 8 * fq;
;                 float ss = 0.f;
; #pragma unroll
;                 for (int bj = 0; bj < 2; ++bj) {
;                     const u32x4 bv = *(const u32x4*)(XB + off + 128 * bj);
;                     f32x4 b0, b1;
;                     b0[0] = __builtin_bit_cast(float, bv[0] << 16); b0[1] = __builtin_bit_cast(float, bv[0] & 0xffff0000u); b0[2] = __builtin_bit_cast(float, bv[1] << 16); b0[3] = __builtin_bit_cast(float, bv[1] & 0xffff0000u);
;                     b1[0] = __builtin_bit_cast(float, bv[2] << 16); b1[1] = __builtin_bit_cast(float, bv[2] & 0xffff0000u); b1[2] = __builtin_bit_cast(float, bv[3] << 16); b1[3] = __builtin_bit_cast(float, bv[3] & 0xffff0000u);
;                     const f32x4 o0 = b0 + acc[ai][bj][m][0], o1 = b1 + acc[ai][bj][m][1];
;                     if (LAST) { *(f32x4*)(out + off + 128 * bj) = o0; *(f32x4*)(out + off + 128 * bj + 4) = o1; }
;                     else {
;                         *(u32x4*)(XB + off + 128 * bj) = pack8(o0, o1);
;                         ss += ((o0[0] * o0[0] + o0[1] * o0[1]) + (o0[2] * o0[2] + o0[3] * o0[3])) + ((o1[0] * o1[0] + o1[1] * o1[1]) + (o1[2] * o1[2] + o1[3] * o1[3]));
;                     }
;                 }
;                 if (!LAST) {
;                     ss += __shfl_xor(ss, 16); ss += __shfl_xor(ss, 32);
;                     if (fq == 0) ssq_out[(size_t)row * 16 + u.pn * 4 + wc] = ss;
;                 }
.LBB0_512:
	s_or_b64 exec, exec, s[38:39]
	v_add_u32_e32 v48, 0x90, v146
	s_waitcnt lgkmcnt(0)
	v_ashrrev_i32_e32 v49, 31, v48
	v_lshlrev_b64 v[50:51], 11, v[48:49]
	v_lshl_add_u64 v[50:51], s[12:13], 0, v[50:51]
	v_lshl_add_u64 v[50:51], s[30:31], 1, v[50:51]
	v_lshl_add_u64 v[50:51], s[36:37], 1, v[50:51]
	v_lshl_add_u64 v[58:59], v[50:51], 0, v[136:137]
	s_nop 1
	v_mov_b32_e32 v50, v214
	v_mov_b32_e32 v51, v215
	v_mov_b32_e32 v52, v216
	v_mov_b32_e32 v53, v217
	s_nop 1
	v_mov_b32_e32 v54, v224
	v_mov_b32_e32 v55, v225
	v_mov_b32_e32 v56, v226
	v_mov_b32_e32 v57, v227
	v_lshlrev_b32_e32 v60, 16, v50
	v_and_b32_e32 v61, 0xffff0000, v50
	v_lshlrev_b32_e32 v50, 16, v51
	v_and_b32_e32 v51, 0xffff0000, v51
	v_lshlrev_b32_e32 v62, 16, v52
	v_and_b32_e32 v63, 0xffff0000, v52
	v_lshlrev_b32_e32 v52, 16, v53
	v_and_b32_e32 v53, 0xffff0000, v53
	v_lshlrev_b32_e32 v64, 16, v54
	v_and_b32_e32 v65, 0xffff0000, v54
	v_lshlrev_b32_e32 v54, 16, v55
	v_and_b32_e32 v55, 0xffff0000, v55
	v_lshlrev_b32_e32 v66, 16, v56
	v_and_b32_e32 v67, 0xffff0000, v56
	v_lshlrev_b32_e32 v56, 16, v57
	v_and_b32_e32 v57, 0xffff0000, v57
	v_pk_add_f32 v[46:47], v[46:47], v[50:51]
	v_pk_add_f32 v[44:45], v[44:45], v[60:61]
	v_pk_add_f32 v[42:43], v[42:43], v[52:53]
	v_pk_add_f32 v[40:41], v[40:41], v[62:63]
	v_pk_add_f32 v[38:39], v[38:39], v[54:55]
	v_pk_add_f32 v[36:37], v[36:37], v[64:65]
	v_pk_add_f32 v[50:51], v[34:35], v[56:57]
	v_pk_add_f32 v[52:53], v[32:33], v[66:67]
	v_cvt_pk_bf16_f32 v32, v44, v45
	v_cvt_pk_bf16_f32 v33, v46, v47
	v_mul_f32_e32 v34, v45, v45
	v_mul_f32_e32 v35, v47, v47
	v_mul_f32_e32 v45, v41, v41
	v_mul_f32_e32 v47, v43, v43
	v_mul_f32_e32 v54, v37, v37
	v_mul_f32_e32 v55, v39, v39
	v_mul_f32_e32 v56, v53, v53
	v_mul_f32_e32 v57, v51, v51
	v_fmac_f32_e32 v34, v44, v44
	v_fmac_f32_e32 v35, v46, v46
	v_fmac_f32_e32 v45, v40, v40
	v_fmac_f32_e32 v47, v42, v42
	v_fmac_f32_e32 v54, v36, v36
	v_fmac_f32_e32 v55, v38, v38
	v_fmac_f32_e32 v56, v52, v52
	v_fmac_f32_e32 v57, v50, v50
	v_add_f32_e32 v34, v34, v35
	v_add_f32_e32 v35, v45, v47
	v_add_f32_e32 v44, v54, v55
	v_add_f32_e32 v45, v56, v57
	v_add_f32_e32 v34, v34, v35
	v_add_f32_e32 v35, v44, v45
	v_add_f32_e32 v44, v34, v35
	ds_bpermute_b32 v45, v154, v44
	v_cvt_pk_bf16_f32 v34, v40, v41
	v_cvt_pk_bf16_f32 v35, v42, v43
	global_store_dwordx4 v[58:59], v[32:35], off
	s_waitcnt lgkmcnt(0)
	s_nop 0
	v_add_f32_e32 v32, v44, v45
	ds_bpermute_b32 v33, v153, v32
	v_cvt_pk_bf16_f32 v34, v36, v37
	v_cvt_pk_bf16_f32 v35, v38, v39
	v_cvt_pk_bf16_f32 v36, v52, v53
	v_cvt_pk_bf16_f32 v37, v50, v51
	global_store_dwordx4 v[58:59], v[34:37], off offset:256
	s_and_saveexec_b64 s[38:39], vcc
	s_cbranch_execz .LBB0_514
	s_waitcnt lgkmcnt(0)
	v_add_f32_e32 v34, v32, v33
	v_lshlrev_b64 v[32:33], 6, v[48:49]
	v_lshl_add_u64 v[32:33], s[14:15], 0, v[32:33]
	v_lshl_add_u64 v[32:33], s[28:29], 2, v[32:33]
	v_lshl_add_u64 v[32:33], s[34:35], 2, v[32:33]
	global_store_dword v[32:33], v34, off
; __device__ __forceinline__ u32x4 pack8(f32x4 a, f32x4 b) { u32x4 w; w.x = cvt_pk_bf16(a[0], a[1]); w.y = cvt_pk_bf16(a[2], a[3]); w.z = cvt_pk_bf16(b[0], b[1]); w.w = cvt_pk_bf16(b[2], b[3]); return w; }
;     __device__ __forceinline__ void operator()(const AccT& acc, const pg8::Unit& u, int wr, int wc, int fr, int fq) const {
;     ...
;         for (int ai = 0; ai < 2; ++ai)
; #pragma unroll
;             for (int m = 0; m < 4; ++m) {
;                 const int row = u.pm * 256 + ai * 128 + wr * 64 + m * 16 + fr;
;                 const size_t off = (size_t)row * 1024 + u.pn * 256 + 32 * wc + 8 * fq;
;                 float ss = 0.f;
; #pragma unroll
;                 for (int bj = 0; bj < 2; ++bj) {
;                     const u32x4 bv = *(const u32x4*)(XB + off + 128 * bj);
;                     f32x4 b0, b1;
;                     b0[0] = __builtin_bit_cast(float, bv[0] << 16); b0[1] = __builtin_bit_cast(float, bv[0] & 0xffff0000u); b0[2] = __builtin_bit_cast(float, bv[1] << 16); b0[3] = __builtin_bit_cast(float, bv[1] & 0xffff0000u);
;                     b1[0] = __builtin_bit_cast(float, bv[2] << 16); b1[1] = __builtin_bit_cast(float, bv[2] & 0xffff0000u); b1[2] = __builtin_bit_cast(float, bv[3] << 16); b1[3] = __builtin_bit_cast(float, bv[3] & 0xffff0000u);
;                     const f32x4 o0 = b0 + acc[ai][bj][m][0], o1 = b1 + acc[ai][bj][m][1];
;                     if (LAST) { *(f32x4*)(out + off + 128 * bj) = o0; *(f32x4*)(out + off + 128 * bj + 4) = o1; }
;                     else {
;                         *(u32x4*)(XB + off + 128 * bj) = pack8(o0, o1);
;                         ss += ((o0[0] * o0[0] + o0[1] * o0[1]) + (o0[2] * o0[2] + o0[3] * o0[3])) + ((o1[0] * o1[0] + o1[1] * o1[1]) + (o1[2] * o1[2] + o1[3] * o1[3]));
;                     }
;                 }
;                 if (!LAST) {
;                     ss += __shfl_xor(ss, 16); ss += __shfl_xor(ss, 32);
;                     if (fq == 0) ssq_out[(size_t)row * 16 + u.pn * 4 + wc] = ss;
;                 }
.LBB0_514:
	s_or_b64 exec, exec, s[38:39]
	v_add_u32_e32 v32, 0xa0, v146
	s_waitcnt lgkmcnt(0)
	v_ashrrev_i32_e32 v33, 31, v32
	v_lshlrev_b64 v[34:35], 11, v[32:33]
	v_lshl_add_u64 v[34:35], s[12:13], 0, v[34:35]
	v_lshl_add_u64 v[34:35], s[30:31], 1, v[34:35]
	v_lshl_add_u64 v[34:35], s[36:37], 1, v[34:35]
	v_lshl_add_u64 v[42:43], v[34:35], 0, v[136:137]
	s_nop 1
	v_mov_b32_e32 v34, v228
	v_mov_b32_e32 v35, v229
	v_mov_b32_e32 v36, v230
	v_mov_b32_e32 v37, v231
	s_nop 1
	v_mov_b32_e32 v38, v232
	v_mov_b32_e32 v39, v233
	v_mov_b32_e32 v40, v234
	v_mov_b32_e32 v41, v235
	v_lshlrev_b32_e32 v44, 16, v34
	v_and_b32_e32 v45, 0xffff0000, v34
	v_lshlrev_b32_e32 v34, 16, v35
	v_and_b32_e32 v35, 0xffff0000, v35
	v_lshlrev_b32_e32 v46, 16, v36
	v_and_b32_e32 v47, 0xffff0000, v36
	v_lshlrev_b32_e32 v36, 16, v37
	v_and_b32_e32 v37, 0xffff0000, v37
	v_lshlrev_b32_e32 v48, 16, v38
	v_and_b32_e32 v49, 0xffff0000, v38
	v_lshlrev_b32_e32 v38, 16, v39
	v_and_b32_e32 v39, 0xffff0000, v39
	v_lshlrev_b32_e32 v50, 16, v40
	v_and_b32_e32 v51, 0xffff0000, v40
	v_lshlrev_b32_e32 v40, 16, v41
	v_and_b32_e32 v41, 0xffff0000, v41
	v_pk_add_f32 v[30:31], v[30:31], v[34:35]
	v_pk_add_f32 v[28:29], v[28:29], v[44:45]
	v_pk_add_f32 v[26:27], v[26:27], v[36:37]
	v_pk_add_f32 v[24:25], v[24:25], v[46:47]
	v_pk_add_f32 v[22:23], v[22:23], v[38:39]
	v_pk_add_f32 v[20:21], v[20:21], v[48:49]
	v_pk_add_f32 v[34:35], v[18:19], v[40:41]
	v_pk_add_f32 v[36:37], v[16:17], v[50:51]
	v_cvt_pk_bf16_f32 v16, v28, v29
	v_cvt_pk_bf16_f32 v17, v30, v31
	v_mul_f32_e32 v18, v29, v29
	v_mul_f32_e32 v19, v31, v31
	v_mul_f32_e32 v29, v25, v25
	v_mul_f32_e32 v31, v27, v27
	v_mul_f32_e32 v38, v21, v21
	v_mul_f32_e32 v39, v23, v23
	v_mul_f32_e32 v40, v37, v37
	v_mul_f32_e32 v41, v35, v35
	v_fmac_f32_e32 v18, v28, v28
	v_fmac_f32_e32 v19, v30, v30
	v_fmac_f32_e32 v29, v24, v24
	v_fmac_f32_e32 v31, v26, v26
	v_fmac_f32_e32 v38, v20, v20
	v_fmac_f32_e32 v39, v22, v22
	v_fmac_f32_e32 v40, v36, v36
	v_fmac_f32_e32 v41, v34, v34
	v_add_f32_e32 v18, v18, v19
	v_add_f32_e32 v19, v29, v31
	v_add_f32_e32 v28, v38, v39
	v_add_f32_e32 v29, v40, v41
	v_add_f32_e32 v18, v18, v19
	v_add_f32_e32 v19, v28, v29
	v_add_f32_e32 v28, v18, v19
	ds_bpermute_b32 v29, v154, v28
	v_cvt_pk_bf16_f32 v18, v24, v25
	v_cvt_pk_bf16_f32 v19, v26, v27
	global_store_dwordx4 v[42:43], v[16:19], off
	s_waitcnt lgkmcnt(0)
	s_nop 0
	v_add_f32_e32 v16, v28, v29
	ds_bpermute_b32 v17, v153, v16
	v_cvt_pk_bf16_f32 v18, v20, v21
	v_cvt_pk_bf16_f32 v19, v22, v23
	v_cvt_pk_bf16_f32 v20, v36, v37
	v_cvt_pk_bf16_f32 v21, v34, v35
	global_store_dwordx4 v[42:43], v[18:21], off offset:256
	s_and_saveexec_b64 s[38:39], vcc
	s_cbranch_execz .LBB0_516
	s_waitcnt lgkmcnt(0)
	v_add_f32_e32 v18, v16, v17
	v_lshlrev_b64 v[16:17], 6, v[32:33]
	v_lshl_add_u64 v[16:17], s[14:15], 0, v[16:17]
	v_lshl_add_u64 v[16:17], s[28:29], 2, v[16:17]
	v_lshl_add_u64 v[16:17], s[34:35], 2, v[16:17]
	global_store_dword v[16:17], v18, off
.LBB0_516:
	s_or_b64 exec, exec, s[38:39]
	v_add_u32_e32 v16, 0xb0, v146
	s_waitcnt lgkmcnt(0)
	v_ashrrev_i32_e32 v17, 31, v16
	v_lshlrev_b64 v[18:19], 11, v[16:17]
	v_lshl_add_u64 v[18:19], s[12:13], 0, v[18:19]
	v_lshl_add_u64 v[18:19], s[30:31], 1, v[18:19]
	v_lshl_add_u64 v[18:19], s[36:37], 1, v[18:19]
	v_lshl_add_u64 v[26:27], v[18:19], 0, v[136:137]
	s_nop 1
	v_mov_b32_e32 v18, v236
	v_mov_b32_e32 v19, v237
	v_mov_b32_e32 v20, v238
	v_mov_b32_e32 v21, v239
	s_nop 1
	v_mov_b32_e32 v22, v240
	v_mov_b32_e32 v23, v241
	v_mov_b32_e32 v24, v242
	v_mov_b32_e32 v25, v243
	v_lshlrev_b32_e32 v28, 16, v18
	v_and_b32_e32 v29, 0xffff0000, v18
	v_lshlrev_b32_e32 v18, 16, v19
	v_and_b32_e32 v19, 0xffff0000, v19
	v_lshlrev_b32_e32 v30, 16, v20
	v_and_b32_e32 v31, 0xffff0000, v20
	v_lshlrev_b32_e32 v20, 16, v21
	v_and_b32_e32 v21, 0xffff0000, v21
	v_lshlrev_b32_e32 v32, 16, v22
	v_and_b32_e32 v33, 0xffff0000, v22
	v_lshlrev_b32_e32 v22, 16, v23
	v_and_b32_e32 v23, 0xffff0000, v23
	v_lshlrev_b32_e32 v34, 16, v24
	v_and_b32_e32 v35, 0xffff0000, v24
	v_lshlrev_b32_e32 v24, 16, v25
	v_and_b32_e32 v25, 0xffff0000, v25
	v_pk_add_f32 v[14:15], v[14:15], v[18:19]
	v_pk_add_f32 v[12:13], v[12:13], v[28:29]
	v_pk_add_f32 v[10:11], v[10:11], v[20:21]
	v_pk_add_f32 v[8:9], v[8:9], v[30:31]
	v_pk_add_f32 v[6:7], v[6:7], v[22:23]
	v_pk_add_f32 v[4:5], v[4:5], v[32:33]
	v_pk_add_f32 v[18:19], v[2:3], v[24:25]
	v_pk_add_f32 v[20:21], v[0:1], v[34:35]
	v_cvt_pk_bf16_f32 v0, v12, v13
	v_cvt_pk_bf16_f32 v1, v14, v15
	v_mul_f32_e32 v2, v13, v13
	v_mul_f32_e32 v3, v15, v15
	v_mul_f32_e32 v13, v9, v9
	v_mul_f32_e32 v15, v11, v11
	v_mul_f32_e32 v22, v5, v5
	v_mul_f32_e32 v23, v7, v7
	v_mul_f32_e32 v24, v21, v21
	v_mul_f32_e32 v25, v19, v19
	v_fmac_f32_e32 v2, v12, v12
	v_fmac_f32_e32 v3, v14, v14
	v_fmac_f32_e32 v13, v8, v8
	v_fmac_f32_e32 v15, v10, v10
	v_fmac_f32_e32 v22, v4, v4
	v_fmac_f32_e32 v23, v6, v6
	v_fmac_f32_e32 v24, v20, v20
	v_fmac_f32_e32 v25, v18, v18
	v_add_f32_e32 v2, v2, v3
	v_add_f32_e32 v3, v13, v15
	v_add_f32_e32 v12, v22, v23
	v_add_f32_e32 v13, v24, v25
	v_add_f32_e32 v2, v2, v3
	v_add_f32_e32 v3, v12, v13
	v_add_f32_e32 v12, v2, v3
	ds_bpermute_b32 v13, v154, v12
	v_cvt_pk_bf16_f32 v2, v8, v9
	v_cvt_pk_bf16_f32 v3, v10, v11
	global_store_dwordx4 v[26:27], v[0:3], off
	s_waitcnt lgkmcnt(0)
	s_nop 0
	v_add_f32_e32 v0, v12, v13
	ds_bpermute_b32 v1, v153, v0
	v_cvt_pk_bf16_f32 v2, v4, v5
	v_cvt_pk_bf16_f32 v3, v6, v7
	v_cvt_pk_bf16_f32 v4, v20, v21
	v_cvt_pk_bf16_f32 v5, v18, v19
	global_store_dwordx4 v[26:27], v[2:5], off offset:256
	s_and_saveexec_b64 s[30:31], vcc
	s_cbranch_execz .LBB0_518
	s_waitcnt lgkmcnt(0)
	v_add_f32_e32 v2, v0, v1
	v_lshlrev_b64 v[0:1], 6, v[16:17]
	v_lshl_add_u64 v[0:1], s[14:15], 0, v[0:1]
	v_lshl_add_u64 v[0:1], s[28:29], 2, v[0:1]
	v_lshl_add_u64 v[0:1], s[34:35], 2, v[0:1]
	global_store_dword v[0:1], v2, off

; __device__ __forceinline__ u32x4 pack8(f32x4 a, f32x4 b) { u32x4 w; w.x = cvt_pk_bf16(a[0], a[1]); w.y = cvt_pk_bf16(a[2], a[3]); w.z = cvt_pk_bf16(b[0], b[1]); w.w = cvt_pk_bf16(b[2], b[3]); return w; }
;     __device__ __forceinline__ void operator()(const AccT& acc, const pg8::Unit& u, int wr, int wc, int fr, int fq) const {
;     ...
;                 const int row = u.pm * 256 + ai * 128 + wr * 64 + m * 16 + fr;
;                 const size_t off = (size_t)row * 1024 + u.pn * 256 + 32 * wc + 8 * fq;
;                 float ss = 0.f;
; #pragma unroll
;                 for (int bj = 0; bj < 2; ++bj) {
;                     const u32x4 bv = *(const u32x4*)(XB + off + 128 * bj);
;                     f32x4 b0, b1;
;                     b0[0] = __builtin_bit_cast(float, bv[0] << 16); b0[1] = __builtin_bit_cast(float, bv[0] & 0xffff0000u); b0[2] = __builtin_bit_cast(float, bv[1] << 16); b0[3] = __builtin_bit_cast(float, bv[1] & 0xffff0000u);
;                     b1[0] = __builtin_bit_cast(float, bv[2] << 16); b1[1] = __builtin_bit_cast(float, bv[2] & 0xffff0000u); b1[2] = __builtin_bit_cast(float, bv[3] << 16); b1[3] = __builtin_bit_cast(float, bv[3] & 0xffff0000u);
;                     const f32x4 o0 = b0 + acc[ai][bj][m][0], o1 = b1 + acc[ai][bj][m][1];
;                     if (LAST) { *(f32x4*)(out + off + 128 * bj) = o0; *(f32x4*)(out + off + 128 * bj + 4) = o1; }
;                     else {
;                         *(u32x4*)(XB + off + 128 * bj) = pack8(o0, o1);
;                         ss += ((o0[0] * o0[0] + o0[1] * o0[1]) + (o0[2] * o0[2] + o0[3] * o0[3])) + ((o1[0] * o1[0] + o1[1] * o1[1]) + (o1[2] * o1[2] + o1[3] * o1[3]));
;                     }
;                 }
;                 if (!LAST) {
;                     ss += __shfl_xor(ss, 16); ss += __shfl_xor(ss, 32);
;                     if (fq == 0) ssq_out[(size_t)row * 16 + u.pn * 4 + wc] = ss;
;                 }
.LBB0_730:
	v_mov_b32_e32 v132, v220
	s_mov_b32 s24, s53
	s_mov_b32 s25, s40
	s_lshl_b32 s26, s35, 8
	s_lshl_b32 s25, s25, 6
	s_add_i32 s25, s25, s26
	v_and_or_b32 v138, v132, 15, s25
	v_ashrrev_i32_e32 v139, 31, v138
	s_lshl_b32 s28, s34, 8
	v_lshlrev_b64 v[148:149], 11, v[138:139]
	s_ashr_i32 s29, s28, 31
	s_lshl_b32 s30, s24, 5
	v_lshl_add_u64 v[148:149], s[16:17], 0, v[148:149]
	v_bfe_u32 v147, v132, 4, 2
	s_ashr_i32 s31, s30, 31
	v_lshl_add_u64 v[148:149], s[28:29], 1, v[148:149]
	v_lshl_add_u64 v[148:149], s[30:31], 1, v[148:149]
	v_lshlrev_b32_e32 v132, 4, v147
	v_lshl_add_u64 v[156:157], v[148:149], 0, v[132:133]
	s_mov_b32 s88, 0x8000
	s_mov_b32 s89, 0
	s_mov_b32 s90, 0x28000
	s_mov_b32 s91, 0
	global_load_dwordx4 v[166:169], v[156:157], off
	global_load_dwordx4 v[170:173], v[156:157], off offset:256
	v_lshl_add_u64 v[234:235], v[156:157], 0, s[88:89]
	global_load_dwordx4 v[174:177], v[234:235], off
	global_load_dwordx4 v[178:181], v[234:235], off offset:256
	v_lshl_add_u64 v[234:235], v[234:235], 0, s[88:89]
	global_load_dwordx4 v[182:185], v[234:235], off
	global_load_dwordx4 v[186:189], v[234:235], off offset:256
	v_lshl_add_u64 v[234:235], v[234:235], 0, s[88:89]
	global_load_dwordx4 v[190:193], v[234:235], off
	global_load_dwordx4 v[194:197], v[234:235], off offset:256
	v_lshl_add_u64 v[234:235], v[234:235], 0, s[90:91]
	global_load_dwordx4 v[198:201], v[234:235], off
	global_load_dwordx4 v[202:205], v[234:235], off offset:256
	v_lshl_add_u64 v[234:235], v[234:235], 0, s[88:89]
	global_load_dwordx4 v[206:209], v[234:235], off
	global_load_dwordx4 v[210:213], v[234:235], off offset:256
	v_lshl_add_u64 v[234:235], v[234:235], 0, s[88:89]
	global_load_dwordx4 v[214:217], v[234:235], off
	global_load_dwordx4 v[222:225], v[234:235], off offset:256
	v_lshl_add_u64 v[234:235], v[234:235], 0, s[88:89]
	global_load_dwordx4 v[226:229], v[234:235], off
	global_load_dwordx4 v[230:233], v[234:235], off offset:256
	s_waitcnt vmcnt(0)
	s_nop 1
	v_mov_b32_e32 v148, v166
	v_mov_b32_e32 v149, v167
	v_mov_b32_e32 v150, v168
	v_mov_b32_e32 v151, v169
	s_nop 1
	v_mov_b32_e32 v152, v170
	v_mov_b32_e32 v153, v171
	v_mov_b32_e32 v154, v172
	v_mov_b32_e32 v155, v173
	v_and_b32_e32 v145, 64, v144
	v_xor_b32_e32 v132, 16, v144
	v_add_u32_e32 v145, 64, v145
	v_xor_b32_e32 v146, 32, v144
	v_cmp_lt_i32_e32 vcc, v132, v145
	s_lshl_b32 s26, s34, 2
	s_ashr_i32 s27, s26, 31
	v_cndmask_b32_e32 v132, v144, v132, vcc
	v_cmp_lt_i32_e32 vcc, v146, v145
	s_ashr_i32 s25, s24, 31
	v_lshlrev_b32_e32 v158, 16, v148
	v_and_b32_e32 v159, 0xffff0000, v148
	v_lshlrev_b32_e32 v148, 16, v149
	v_and_b32_e32 v149, 0xffff0000, v149
	v_lshlrev_b32_e32 v160, 16, v150
	v_and_b32_e32 v161, 0xffff0000, v150
	v_lshlrev_b32_e32 v150, 16, v151
	v_and_b32_e32 v151, 0xffff0000, v151
	v_lshlrev_b32_e32 v162, 16, v152
	v_and_b32_e32 v163, 0xffff0000, v152
	v_lshlrev_b32_e32 v152, 16, v153
	v_and_b32_e32 v153, 0xffff0000, v153
	v_lshlrev_b32_e32 v164, 16, v154
	v_and_b32_e32 v165, 0xffff0000, v154
	v_lshlrev_b32_e32 v154, 16, v155
	v_and_b32_e32 v155, 0xffff0000, v155
	v_pk_add_f32 v[126:127], v[126:127], v[148:149]
	v_pk_add_f32 v[124:125], v[124:125], v[158:159]
	v_pk_add_f32 v[122:123], v[122:123], v[150:151]
	v_pk_add_f32 v[120:121], v[120:121], v[160:161]
	v_pk_add_f32 v[118:119], v[118:119], v[152:153]
	v_pk_add_f32 v[116:117], v[116:117], v[162:163]
	v_pk_add_f32 v[148:149], v[114:115], v[154:155]
	v_pk_add_f32 v[150:151], v[112:113], v[164:165]
	v_cndmask_b32_e32 v145, v144, v146, vcc
	v_lshlrev_b32_e32 v146, 2, v132
	v_cvt_pk_bf16_f32 v112, v124, v125
	v_cvt_pk_bf16_f32 v113, v126, v127
	v_mul_f32_e32 v114, v125, v125
	v_mul_f32_e32 v115, v127, v127
	v_mul_f32_e32 v125, v121, v121
	v_mul_f32_e32 v127, v123, v123
	v_mul_f32_e32 v132, v117, v117
	v_mul_f32_e32 v152, v119, v119
	v_mul_f32_e32 v153, v151, v151
	v_mul_f32_e32 v154, v149, v149
	v_fmac_f32_e32 v114, v124, v124
	v_fmac_f32_e32 v115, v126, v126
	v_fmac_f32_e32 v125, v120, v120
	v_fmac_f32_e32 v127, v122, v122
	v_fmac_f32_e32 v132, v116, v116
	v_fmac_f32_e32 v152, v118, v118
	v_fmac_f32_e32 v153, v150, v150
	v_fmac_f32_e32 v154, v148, v148
	v_add_f32_e32 v114, v114, v115
	v_add_f32_e32 v115, v125, v127
	v_add_f32_e32 v124, v132, v152
	v_add_f32_e32 v125, v153, v154
	v_add_f32_e32 v114, v114, v115
	v_add_f32_e32 v115, v124, v125
	v_add_f32_e32 v124, v114, v115
	ds_bpermute_b32 v125, v146, v124
	v_cvt_pk_bf16_f32 v114, v120, v121
	v_cvt_pk_bf16_f32 v115, v122, v123
	v_lshlrev_b32_e32 v145, 2, v145
	global_store_dwordx4 v[156:157], v[112:115], off
	v_cmp_eq_u32_e32 vcc, 0, v147
	s_waitcnt lgkmcnt(0)
	v_add_f32_e32 v112, v124, v125
	ds_bpermute_b32 v113, v145, v112
	v_cvt_pk_bf16_f32 v114, v116, v117
	v_cvt_pk_bf16_f32 v115, v118, v119
	v_cvt_pk_bf16_f32 v116, v150, v151
	v_cvt_pk_bf16_f32 v117, v148, v149
	global_store_dwordx4 v[156:157], v[114:117], off offset:256
	s_and_saveexec_b64 s[34:35], vcc
	s_cbranch_execz .LBB0_732
	s_waitcnt lgkmcnt(0)
	v_add_f32_e32 v114, v112, v113
	v_lshlrev_b64 v[112:113], 6, v[138:139]
	v_lshl_add_u64 v[112:113], s[18:19], 0, v[112:113]
	v_lshl_add_u64 v[112:113], s[26:27], 2, v[112:113]
	v_lshl_add_u64 v[112:113], s[24:25], 2, v[112:113]
	global_store_dword v[112:113], v114, off
; __device__ __forceinline__ u32x4 pack8(f32x4 a, f32x4 b) { u32x4 w; w.x = cvt_pk_bf16(a[0], a[1]); w.y = cvt_pk_bf16(a[2], a[3]); w.z = cvt_pk_bf16(b[0], b[1]); w.w = cvt_pk_bf16(b[2], b[3]); return w; }
;     __device__ __forceinline__ void operator()(const AccT& acc, const pg8::Unit& u, int wr, int wc, int fr, int fq) const {
;     ...
;                 const int row = u.pm * 256 + ai * 128 + wr * 64 + m * 16 + fr;
;                 const size_t off = (size_t)row * 1024 + u.pn * 256 + 32 * wc + 8 * fq;
;                 float ss = 0.f;
; #pragma unroll
;                 for (int bj = 0; bj < 2; ++bj) {
;                     const u32x4 bv = *(const u32x4*)(XB + off + 128 * bj);
;                     f32x4 b0, b1;
;                     b0[0] = __builtin_bit_cast(float, bv[0] << 16); b0[1] = __builtin_bit_cast(float, bv[0] & 0xffff0000u); b0[2] = __builtin_bit_cast(float, bv[1] << 16); b0[3] = __builtin_bit_cast(float, bv[1] & 0xffff0000u);
;                     b1[0] = __builtin_bit_cast(float, bv[2] << 16); b1[1] = __builtin_bit_cast(float, bv[2] & 0xffff0000u); b1[2] = __builtin_bit_cast(float, bv[3] << 16); b1[3] = __builtin_bit_cast(float, bv[3] & 0xffff0000u);
;                     const f32x4 o0 = b0 + acc[ai][bj][m][0], o1 = b1 + acc[ai][bj][m][1];
;                     if (LAST) { *(f32x4*)(out + off + 128 * bj) = o0; *(f32x4*)(out + off + 128 * bj + 4) = o1; }
;                     else {
;                         *(u32x4*)(XB + off + 128 * bj) = pack8(o0, o1);
;                         ss += ((o0[0] * o0[0] + o0[1] * o0[1]) + (o0[2] * o0[2] + o0[3] * o0[3])) + ((o1[0] * o1[0] + o1[1] * o1[1]) + (o1[2] * o1[2] + o1[3] * o1[3]));
;                     }
;                 }
;                 if (!LAST) {
;                     ss += __shfl_xor(ss, 16); ss += __shfl_xor(ss, 32);
;                     if (fq == 0) ssq_out[(size_t)row * 16 + u.pn * 4 + wc] = ss;
;                 }
.LBB0_732:
	s_or_b64 exec, exec, s[34:35]
	v_or_b32_e32 v112, 16, v138
	s_waitcnt lgkmcnt(0)
	v_ashrrev_i32_e32 v113, 31, v112
	v_lshlrev_b64 v[114:115], 11, v[112:113]
	v_lshl_add_u64 v[114:115], s[16:17], 0, v[114:115]
	v_lshlrev_b32_e32 v116, 3, v147
	v_lshl_add_u64 v[114:115], s[28:29], 1, v[114:115]
	v_lshl_add_u64 v[114:115], s[30:31], 1, v[114:115]
	v_lshlrev_b32_e32 v132, 1, v116
	v_lshl_add_u64 v[122:123], v[114:115], 0, v[132:133]
	s_nop 1
	v_mov_b32_e32 v114, v174
	v_mov_b32_e32 v115, v175
	v_mov_b32_e32 v116, v176
	v_mov_b32_e32 v117, v177
	s_nop 1
	v_mov_b32_e32 v118, v178
	v_mov_b32_e32 v119, v179
	v_mov_b32_e32 v120, v180
	v_mov_b32_e32 v121, v181
	v_lshlrev_b32_e32 v124, 16, v114
	v_and_b32_e32 v125, 0xffff0000, v114
	v_lshlrev_b32_e32 v114, 16, v115
	v_and_b32_e32 v115, 0xffff0000, v115
	v_lshlrev_b32_e32 v126, 16, v116
	v_and_b32_e32 v127, 0xffff0000, v116
	v_lshlrev_b32_e32 v116, 16, v117
	v_and_b32_e32 v117, 0xffff0000, v117
	v_lshlrev_b32_e32 v148, 16, v118
	v_and_b32_e32 v149, 0xffff0000, v118
	v_lshlrev_b32_e32 v118, 16, v119
	v_and_b32_e32 v119, 0xffff0000, v119
	v_lshlrev_b32_e32 v150, 16, v120
	v_and_b32_e32 v151, 0xffff0000, v120
	v_lshlrev_b32_e32 v120, 16, v121
	v_and_b32_e32 v121, 0xffff0000, v121
	v_pk_add_f32 v[110:111], v[110:111], v[114:115]
	v_pk_add_f32 v[108:109], v[108:109], v[124:125]
	v_pk_add_f32 v[106:107], v[106:107], v[116:117]
	v_pk_add_f32 v[104:105], v[104:105], v[126:127]
	v_pk_add_f32 v[102:103], v[102:103], v[118:119]
	v_pk_add_f32 v[100:101], v[100:101], v[148:149]
	v_pk_add_f32 v[114:115], v[98:99], v[120:121]
	v_pk_add_f32 v[116:117], v[96:97], v[150:151]
	v_cvt_pk_bf16_f32 v96, v108, v109
	v_cvt_pk_bf16_f32 v97, v110, v111
	v_mul_f32_e32 v98, v109, v109
	v_mul_f32_e32 v99, v111, v111
	v_mul_f32_e32 v109, v105, v105
	v_mul_f32_e32 v111, v107, v107
	v_mul_f32_e32 v118, v101, v101
	v_mul_f32_e32 v119, v103, v103
	v_mul_f32_e32 v120, v117, v117
	v_mul_f32_e32 v121, v115, v115
	v_fmac_f32_e32 v98, v108, v108
	v_fmac_f32_e32 v99, v110, v110
	v_fmac_f32_e32 v109, v104, v104
	v_fmac_f32_e32 v111, v106, v106
	v_fmac_f32_e32 v118, v100, v100
	v_fmac_f32_e32 v119, v102, v102
	v_fmac_f32_e32 v120, v116, v116
	v_fmac_f32_e32 v121, v114, v114
	v_add_f32_e32 v98, v98, v99
	v_add_f32_e32 v99, v109, v111
	v_add_f32_e32 v108, v118, v119
	v_add_f32_e32 v109, v120, v121
	v_add_f32_e32 v98, v98, v99
	v_add_f32_e32 v99, v108, v109
	v_add_f32_e32 v108, v98, v99
	ds_bpermute_b32 v109, v146, v108
	v_cvt_pk_bf16_f32 v98, v104, v105
	v_cvt_pk_bf16_f32 v99, v106, v107
	global_store_dwordx4 v[122:123], v[96:99], off
	s_waitcnt lgkmcnt(0)
	s_nop 0
	v_add_f32_e32 v96, v108, v109
	ds_bpermute_b32 v97, v145, v96
	v_cvt_pk_bf16_f32 v98, v100, v101
	v_cvt_pk_bf16_f32 v99, v102, v103
	v_cvt_pk_bf16_f32 v100, v116, v117
	v_cvt_pk_bf16_f32 v101, v114, v115
	global_store_dwordx4 v[122:123], v[98:101], off offset:256
	s_and_saveexec_b64 s[34:35], vcc
	s_cbranch_execz .LBB0_734
	s_waitcnt lgkmcnt(0)
	v_add_f32_e32 v98, v96, v97
	v_lshlrev_b64 v[96:97], 6, v[112:113]
	v_lshl_add_u64 v[96:97], s[18:19], 0, v[96:97]
	v_lshl_add_u64 v[96:97], s[26:27], 2, v[96:97]
	v_lshl_add_u64 v[96:97], s[24:25], 2, v[96:97]
	global_store_dword v[96:97], v98, off
.LBB0_734:
	s_or_b64 exec, exec, s[34:35]
	v_or_b32_e32 v96, 32, v138
	s_waitcnt lgkmcnt(0)
	v_ashrrev_i32_e32 v97, 31, v96
	v_lshlrev_b64 v[98:99], 11, v[96:97]
	v_lshl_add_u64 v[98:99], s[16:17], 0, v[98:99]
	v_lshl_add_u64 v[98:99], s[28:29], 1, v[98:99]
	v_lshl_add_u64 v[98:99], s[30:31], 1, v[98:99]
	v_lshl_add_u64 v[106:107], v[98:99], 0, v[132:133]
	s_nop 1
	v_mov_b32_e32 v98, v182
	v_mov_b32_e32 v99, v183
	v_mov_b32_e32 v100, v184
	v_mov_b32_e32 v101, v185
	s_nop 1
	v_mov_b32_e32 v102, v186
	v_mov_b32_e32 v103, v187
	v_mov_b32_e32 v104, v188
	v_mov_b32_e32 v105, v189
	v_lshlrev_b32_e32 v108, 16, v98
	v_and_b32_e32 v109, 0xffff0000, v98
	v_lshlrev_b32_e32 v98, 16, v99
	v_and_b32_e32 v99, 0xffff0000, v99
	v_lshlrev_b32_e32 v110, 16, v100
	v_and_b32_e32 v111, 0xffff0000, v100
	v_lshlrev_b32_e32 v100, 16, v101
	v_and_b32_e32 v101, 0xffff0000, v101
	v_lshlrev_b32_e32 v112, 16, v102
	v_and_b32_e32 v113, 0xffff0000, v102
	v_lshlrev_b32_e32 v102, 16, v103
	v_and_b32_e32 v103, 0xffff0000, v103
	v_lshlrev_b32_e32 v114, 16, v104
	v_and_b32_e32 v115, 0xffff0000, v104
	v_lshlrev_b32_e32 v104, 16, v105
	v_and_b32_e32 v105, 0xffff0000, v105
	v_pk_add_f32 v[94:95], v[94:95], v[98:99]
	v_pk_add_f32 v[92:93], v[92:93], v[108:109]
	v_pk_add_f32 v[90:91], v[90:91], v[100:101]
	v_pk_add_f32 v[88:89], v[88:89], v[110:111]
	v_pk_add_f32 v[86:87], v[86:87], v[102:103]
	v_pk_add_f32 v[84:85], v[84:85], v[112:113]
	v_pk_add_f32 v[98:99], v[82:83], v[104:105]
	v_pk_add_f32 v[100:101], v[80:81], v[114:115]
	v_cvt_pk_bf16_f32 v80, v92, v93
	v_cvt_pk_bf16_f32 v81, v94, v95
	v_mul_f32_e32 v82, v93, v93
	v_mul_f32_e32 v83, v95, v95
	v_mul_f32_e32 v93, v89, v89
	v_mul_f32_e32 v95, v91, v91
	v_mul_f32_e32 v102, v85, v85
	v_mul_f32_e32 v103, v87, v87
	v_mul_f32_e32 v104, v101, v101
	v_mul_f32_e32 v105, v99, v99
	v_fmac_f32_e32 v82, v92, v92
	v_fmac_f32_e32 v83, v94, v94
	v_fmac_f32_e32 v93, v88, v88
	v_fmac_f32_e32 v95, v90, v90
	v_fmac_f32_e32 v102, v84, v84
	v_fmac_f32_e32 v103, v86, v86
	v_fmac_f32_e32 v104, v100, v100
	v_fmac_f32_e32 v105, v98, v98
	v_add_f32_e32 v82, v82, v83
	v_add_f32_e32 v83, v93, v95
	v_add_f32_e32 v92, v102, v103
	v_add_f32_e32 v93, v104, v105
	v_add_f32_e32 v82, v82, v83
	v_add_f32_e32 v83, v92, v93
	v_add_f32_e32 v92, v82, v83
	ds_bpermute_b32 v93, v146, v92
	v_cvt_pk_bf16_f32 v82, v88, v89
	v_cvt_pk_bf16_f32 v83, v90, v91
	global_store_dwordx4 v[106:107], v[80:83], off
	s_waitcnt lgkmcnt(0)
	s_nop 0
	v_add_f32_e32 v80, v92, v93
	ds_bpermute_b32 v81, v145, v80
	v_cvt_pk_bf16_f32 v82, v84, v85
	v_cvt_pk_bf16_f32 v83, v86, v87
	v_cvt_pk_bf16_f32 v84, v100, v101
	v_cvt_pk_bf16_f32 v85, v98, v99
	global_store_dwordx4 v[106:107], v[82:85], off offset:256
	s_and_saveexec_b64 s[34:35], vcc
	s_cbranch_execz .LBB0_736
	s_waitcnt lgkmcnt(0)
	v_add_f32_e32 v82, v80, v81
	v_lshlrev_b64 v[80:81], 6, v[96:97]
	v_lshl_add_u64 v[80:81], s[18:19], 0, v[80:81]
	v_lshl_add_u64 v[80:81], s[26:27], 2, v[80:81]
	v_lshl_add_u64 v[80:81], s[24:25], 2, v[80:81]
	global_store_dword v[80:81], v82, off
; __device__ __forceinline__ u32x4 pack8(f32x4 a, f32x4 b) { u32x4 w; w.x = cvt_pk_bf16(a[0], a[1]); w.y = cvt_pk_bf16(a[2], a[3]); w.z = cvt_pk_bf16(b[0], b[1]); w.w = cvt_pk_bf16(b[2], b[3]); return w; }
;     __device__ __forceinline__ void operator()(const AccT& acc, const pg8::Unit& u, int wr, int wc, int fr, int fq) const {
;     ...
;                 const int row = u.pm * 256 + ai * 128 + wr * 64 + m * 16 + fr;
;                 const size_t off = (size_t)row * 1024 + u.pn * 256 + 32 * wc + 8 * fq;
;                 float ss = 0.f;
; #pragma unroll
;                 for (int bj = 0; bj < 2; ++bj) {
;                     const u32x4 bv = *(const u32x4*)(XB + off + 128 * bj);
;                     f32x4 b0, b1;
;                     b0[0] = __builtin_bit_cast(float, bv[0] << 16); b0[1] = __builtin_bit_cast(float, bv[0] & 0xffff0000u); b0[2] = __builtin_bit_cast(float, bv[1] << 16); b0[3] = __builtin_bit_cast(float, bv[1] & 0xffff0000u);
;                     b1[0] = __builtin_bit_cast(float, bv[2] << 16); b1[1] = __builtin_bit_cast(float, bv[2] & 0xffff0000u); b1[2] = __builtin_bit_cast(float, bv[3] << 16); b1[3] = __builtin_bit_cast(float, bv[3] & 0xffff0000u);
;                     const f32x4 o0 = b0 + acc[ai][bj][m][0], o1 = b1 + acc[ai][bj][m][1];
;                     if (LAST) { *(f32x4*)(out + off + 128 * bj) = o0; *(f32x4*)(out + off + 128 * bj + 4) = o1; }
;                     else {
;                         *(u32x4*)(XB + off + 128 * bj) = pack8(o0, o1);
;                         ss += ((o0[0] * o0[0] + o0[1] * o0[1]) + (o0[2] * o0[2] + o0[3] * o0[3])) + ((o1[0] * o1[0] + o1[1] * o1[1]) + (o1[2] * o1[2] + o1[3] * o1[3]));
;                     }
;                 }
;                 if (!LAST) {
;                     ss += __shfl_xor(ss, 16); ss += __shfl_xor(ss, 32);
;                     if (fq == 0) ssq_out[(size_t)row * 16 + u.pn * 4 + wc] = ss;
;                 }
.LBB0_736:
	s_or_b64 exec, exec, s[34:35]
	v_or_b32_e32 v80, 48, v138
	s_waitcnt lgkmcnt(0)
	v_ashrrev_i32_e32 v81, 31, v80
	v_lshlrev_b64 v[82:83], 11, v[80:81]
	v_lshl_add_u64 v[82:83], s[16:17], 0, v[82:83]
	v_lshl_add_u64 v[82:83], s[28:29], 1, v[82:83]
	v_lshl_add_u64 v[82:83], s[30:31], 1, v[82:83]
	v_lshl_add_u64 v[90:91], v[82:83], 0, v[132:133]
	s_nop 1
	v_mov_b32_e32 v82, v190
	v_mov_b32_e32 v83, v191
	v_mov_b32_e32 v84, v192
	v_mov_b32_e32 v85, v193
	s_nop 1
	v_mov_b32_e32 v86, v194
	v_mov_b32_e32 v87, v195
	v_mov_b32_e32 v88, v196
	v_mov_b32_e32 v89, v197
	v_lshlrev_b32_e32 v92, 16, v82
	v_and_b32_e32 v93, 0xffff0000, v82
	v_lshlrev_b32_e32 v82, 16, v83
	v_and_b32_e32 v83, 0xffff0000, v83
	v_lshlrev_b32_e32 v94, 16, v84
	v_and_b32_e32 v95, 0xffff0000, v84
	v_lshlrev_b32_e32 v84, 16, v85
	v_and_b32_e32 v85, 0xffff0000, v85
	v_lshlrev_b32_e32 v96, 16, v86
	v_and_b32_e32 v97, 0xffff0000, v86
	v_lshlrev_b32_e32 v86, 16, v87
	v_and_b32_e32 v87, 0xffff0000, v87
	v_lshlrev_b32_e32 v98, 16, v88
	v_and_b32_e32 v99, 0xffff0000, v88
	v_lshlrev_b32_e32 v88, 16, v89
	v_and_b32_e32 v89, 0xffff0000, v89
	v_pk_add_f32 v[78:79], v[78:79], v[82:83]
	v_pk_add_f32 v[76:77], v[76:77], v[92:93]
	v_pk_add_f32 v[74:75], v[74:75], v[84:85]
	v_pk_add_f32 v[72:73], v[72:73], v[94:95]
	v_pk_add_f32 v[70:71], v[70:71], v[86:87]
	v_pk_add_f32 v[68:69], v[68:69], v[96:97]
	v_pk_add_f32 v[82:83], v[66:67], v[88:89]
	v_pk_add_f32 v[84:85], v[64:65], v[98:99]
	v_cvt_pk_bf16_f32 v64, v76, v77
	v_cvt_pk_bf16_f32 v65, v78, v79
	v_mul_f32_e32 v66, v77, v77
	v_mul_f32_e32 v67, v79, v79
	v_mul_f32_e32 v77, v73, v73
	v_mul_f32_e32 v79, v75, v75
	v_mul_f32_e32 v86, v69, v69
	v_mul_f32_e32 v87, v71, v71
	v_mul_f32_e32 v88, v85, v85
	v_mul_f32_e32 v89, v83, v83
	v_fmac_f32_e32 v66, v76, v76
	v_fmac_f32_e32 v67, v78, v78
	v_fmac_f32_e32 v77, v72, v72
	v_fmac_f32_e32 v79, v74, v74
	v_fmac_f32_e32 v86, v68, v68
	v_fmac_f32_e32 v87, v70, v70
	v_fmac_f32_e32 v88, v84, v84
	v_fmac_f32_e32 v89, v82, v82
	v_add_f32_e32 v66, v66, v67
	v_add_f32_e32 v67, v77, v79
	v_add_f32_e32 v76, v86, v87
	v_add_f32_e32 v77, v88, v89
	v_add_f32_e32 v66, v66, v67
	v_add_f32_e32 v67, v76, v77
	v_add_f32_e32 v76, v66, v67
	ds_bpermute_b32 v77, v146, v76
	v_cvt_pk_bf16_f32 v66, v72, v73
	v_cvt_pk_bf16_f32 v67, v74, v75
	global_store_dwordx4 v[90:91], v[64:67], off
	s_waitcnt lgkmcnt(0)
	s_nop 0
	v_add_f32_e32 v64, v76, v77
	ds_bpermute_b32 v65, v145, v64
	v_cvt_pk_bf16_f32 v66, v68, v69
	v_cvt_pk_bf16_f32 v67, v70, v71
	v_cvt_pk_bf16_f32 v68, v84, v85
	v_cvt_pk_bf16_f32 v69, v82, v83
	global_store_dwordx4 v[90:91], v[66:69], off offset:256
	s_and_saveexec_b64 s[34:35], vcc
	s_cbranch_execz .LBB0_738
	s_waitcnt lgkmcnt(0)
	v_add_f32_e32 v66, v64, v65
	v_lshlrev_b64 v[64:65], 6, v[80:81]
	v_lshl_add_u64 v[64:65], s[18:19], 0, v[64:65]
	v_lshl_add_u64 v[64:65], s[26:27], 2, v[64:65]
	v_lshl_add_u64 v[64:65], s[24:25], 2, v[64:65]
	global_store_dword v[64:65], v66, off
.LBB0_738:
	s_or_b64 exec, exec, s[34:35]
	v_add_u32_e32 v64, 0x80, v138
	s_waitcnt lgkmcnt(0)
	v_ashrrev_i32_e32 v65, 31, v64
	v_lshlrev_b64 v[66:67], 11, v[64:65]
	v_lshl_add_u64 v[66:67], s[16:17], 0, v[66:67]
	v_lshl_add_u64 v[66:67], s[28:29], 1, v[66:67]
	v_lshl_add_u64 v[66:67], s[30:31], 1, v[66:67]
	v_lshl_add_u64 v[74:75], v[66:67], 0, v[132:133]
	s_nop 1
	v_mov_b32_e32 v66, v198
	v_mov_b32_e32 v67, v199
	v_mov_b32_e32 v68, v200
	v_mov_b32_e32 v69, v201
	s_nop 1
	v_mov_b32_e32 v70, v202
	v_mov_b32_e32 v71, v203
	v_mov_b32_e32 v72, v204
	v_mov_b32_e32 v73, v205
	v_lshlrev_b32_e32 v76, 16, v66
	v_and_b32_e32 v77, 0xffff0000, v66
	v_lshlrev_b32_e32 v66, 16, v67
	v_and_b32_e32 v67, 0xffff0000, v67
	v_lshlrev_b32_e32 v78, 16, v68
	v_and_b32_e32 v79, 0xffff0000, v68
	v_lshlrev_b32_e32 v68, 16, v69
	v_and_b32_e32 v69, 0xffff0000, v69
	v_lshlrev_b32_e32 v80, 16, v70
	v_and_b32_e32 v81, 0xffff0000, v70
	v_lshlrev_b32_e32 v70, 16, v71
	v_and_b32_e32 v71, 0xffff0000, v71
	v_lshlrev_b32_e32 v82, 16, v72
	v_and_b32_e32 v83, 0xffff0000, v72
	v_lshlrev_b32_e32 v72, 16, v73
	v_and_b32_e32 v73, 0xffff0000, v73
	v_pk_add_f32 v[62:63], v[62:63], v[66:67]
	v_pk_add_f32 v[60:61], v[60:61], v[76:77]
	v_pk_add_f32 v[58:59], v[58:59], v[68:69]
	v_pk_add_f32 v[56:57], v[56:57], v[78:79]
	v_pk_add_f32 v[54:55], v[54:55], v[70:71]
	v_pk_add_f32 v[52:53], v[52:53], v[80:81]
	v_pk_add_f32 v[66:67], v[50:51], v[72:73]
	v_pk_add_f32 v[68:69], v[48:49], v[82:83]
	v_cvt_pk_bf16_f32 v48, v60, v61
	v_cvt_pk_bf16_f32 v49, v62, v63
	v_mul_f32_e32 v50, v61, v61
	v_mul_f32_e32 v51, v63, v63
	v_mul_f32_e32 v61, v57, v57
	v_mul_f32_e32 v63, v59, v59
	v_mul_f32_e32 v70, v53, v53
	v_mul_f32_e32 v71, v55, v55
	v_mul_f32_e32 v72, v69, v69
	v_mul_f32_e32 v73, v67, v67
	v_fmac_f32_e32 v50, v60, v60
	v_fmac_f32_e32 v51, v62, v62
	v_fmac_f32_e32 v61, v56, v56
	v_fmac_f32_e32 v63, v58, v58
	v_fmac_f32_e32 v70, v52, v52
	v_fmac_f32_e32 v71, v54, v54
	v_fmac_f32_e32 v72, v68, v68
	v_fmac_f32_e32 v73, v66, v66
	v_add_f32_e32 v50, v50, v51
	v_add_f32_e32 v51, v61, v63
	v_add_f32_e32 v60, v70, v71
	v_add_f32_e32 v61, v72, v73
	v_add_f32_e32 v50, v50, v51
	v_add_f32_e32 v51, v60, v61
	v_add_f32_e32 v60, v50, v51
	ds_bpermute_b32 v61, v146, v60
	v_cvt_pk_bf16_f32 v50, v56, v57
	v_cvt_pk_bf16_f32 v51, v58, v59
	global_store_dwordx4 v[74:75], v[48:51], off
	s_waitcnt lgkmcnt(0)
	s_nop 0
	v_add_f32_e32 v48, v60, v61
	ds_bpermute_b32 v49, v145, v48
	v_cvt_pk_bf16_f32 v50, v52, v53
	v_cvt_pk_bf16_f32 v51, v54, v55
	v_cvt_pk_bf16_f32 v52, v68, v69
	v_cvt_pk_bf16_f32 v53, v66, v67
	global_store_dwordx4 v[74:75], v[50:53], off offset:256
	s_and_saveexec_b64 s[34:35], vcc
	s_cbranch_execz .LBB0_740
	s_waitcnt lgkmcnt(0)
	v_add_f32_e32 v50, v48, v49
	v_lshlrev_b64 v[48:49], 6, v[64:65]
	v_lshl_add_u64 v[48:49], s[18:19], 0, v[48:49]
	v_lshl_add_u64 v[48:49], s[26:27], 2, v[48:49]
	v_lshl_add_u64 v[48:49], s[24:25], 2, v[48:49]
	global_store_dword v[48:49], v50, off
; __device__ __forceinline__ u32x4 pack8(f32x4 a, f32x4 b) { u32x4 w; w.x = cvt_pk_bf16(a[0], a[1]); w.y = cvt_pk_bf16(a[2], a[3]); w.z = cvt_pk_bf16(b[0], b[1]); w.w = cvt_pk_bf16(b[2], b[3]); return w; }
;     __device__ __forceinline__ void operator()(const AccT& acc, const pg8::Unit& u, int wr, int wc, int fr, int fq) const {
;     ...
;                 const int row = u.pm * 256 + ai * 128 + wr * 64 + m * 16 + fr;
;                 const size_t off = (size_t)row * 1024 + u.pn * 256 + 32 * wc + 8 * fq;
;                 float ss = 0.f;
; #pragma unroll
;                 for (int bj = 0; bj < 2; ++bj) {
;                     const u32x4 bv = *(const u32x4*)(XB + off + 128 * bj);
;                     f32x4 b0, b1;
;                     b0[0] = __builtin_bit_cast(float, bv[0] << 16); b0[1] = __builtin_bit_cast(float, bv[0] & 0xffff0000u); b0[2] = __builtin_bit_cast(float, bv[1] << 16); b0[3] = __builtin_bit_cast(float, bv[1] & 0xffff0000u);
;                     b1[0] = __builtin_bit_cast(float, bv[2] << 16); b1[1] = __builtin_bit_cast(float, bv[2] & 0xffff0000u); b1[2] = __builtin_bit_cast(float, bv[3] << 16); b1[3] = __builtin_bit_cast(float, bv[3] & 0xffff0000u);
;                     const f32x4 o0 = b0 + acc[ai][bj][m][0], o1 = b1 + acc[ai][bj][m][1];
;                     if (LAST) { *(f32x4*)(out + off + 128 * bj) = o0; *(f32x4*)(out + off + 128 * bj + 4) = o1; }
;                     else {
;                         *(u32x4*)(XB + off + 128 * bj) = pack8(o0, o1);
;                         ss += ((o0[0] * o0[0] + o0[1] * o0[1]) + (o0[2] * o0[2] + o0[3] * o0[3])) + ((o1[0] * o1[0] + o1[1] * o1[1]) + (o1[2] * o1[2] + o1[3] * o1[3]));
;                     }
;                 }
;                 if (!LAST) {
;                     ss += __shfl_xor(ss, 16); ss += __shfl_xor(ss, 32);
;                     if (fq == 0) ssq_out[(size_t)row * 16 + u.pn * 4 + wc] = ss;
;                 }
.LBB0_740:
	s_or_b64 exec, exec, s[34:35]
	v_add_u32_e32 v48, 0x90, v138
	s_waitcnt lgkmcnt(0)
	v_ashrrev_i32_e32 v49, 31, v48
	v_lshlrev_b64 v[50:51], 11, v[48:49]
	v_lshl_add_u64 v[50:51], s[16:17], 0, v[50:51]
	v_lshl_add_u64 v[50:51], s[28:29], 1, v[50:51]
	v_lshl_add_u64 v[50:51], s[30:31], 1, v[50:51]
	v_lshl_add_u64 v[58:59], v[50:51], 0, v[132:133]
	s_nop 1
	v_mov_b32_e32 v50, v206
	v_mov_b32_e32 v51, v207
	v_mov_b32_e32 v52, v208
	v_mov_b32_e32 v53, v209
	s_nop 1
	v_mov_b32_e32 v54, v210
	v_mov_b32_e32 v55, v211
	v_mov_b32_e32 v56, v212
	v_mov_b32_e32 v57, v213
	v_lshlrev_b32_e32 v60, 16, v50
	v_and_b32_e32 v61, 0xffff0000, v50
	v_lshlrev_b32_e32 v50, 16, v51
	v_and_b32_e32 v51, 0xffff0000, v51
	v_lshlrev_b32_e32 v62, 16, v52
	v_and_b32_e32 v63, 0xffff0000, v52
	v_lshlrev_b32_e32 v52, 16, v53
	v_and_b32_e32 v53, 0xffff0000, v53
	v_lshlrev_b32_e32 v64, 16, v54
	v_and_b32_e32 v65, 0xffff0000, v54
	v_lshlrev_b32_e32 v54, 16, v55
	v_and_b32_e32 v55, 0xffff0000, v55
	v_lshlrev_b32_e32 v66, 16, v56
	v_and_b32_e32 v67, 0xffff0000, v56
	v_lshlrev_b32_e32 v56, 16, v57
	v_and_b32_e32 v57, 0xffff0000, v57
	v_pk_add_f32 v[46:47], v[46:47], v[50:51]
	v_pk_add_f32 v[44:45], v[44:45], v[60:61]
	v_pk_add_f32 v[42:43], v[42:43], v[52:53]
	v_pk_add_f32 v[40:41], v[40:41], v[62:63]
	v_pk_add_f32 v[38:39], v[38:39], v[54:55]
	v_pk_add_f32 v[36:37], v[36:37], v[64:65]
	v_pk_add_f32 v[50:51], v[34:35], v[56:57]
	v_pk_add_f32 v[52:53], v[32:33], v[66:67]
	v_cvt_pk_bf16_f32 v32, v44, v45
	v_cvt_pk_bf16_f32 v33, v46, v47
	v_mul_f32_e32 v34, v45, v45
	v_mul_f32_e32 v35, v47, v47
	v_mul_f32_e32 v45, v41, v41
	v_mul_f32_e32 v47, v43, v43
	v_mul_f32_e32 v54, v37, v37
	v_mul_f32_e32 v55, v39, v39
	v_mul_f32_e32 v56, v53, v53
	v_mul_f32_e32 v57, v51, v51
	v_fmac_f32_e32 v34, v44, v44
	v_fmac_f32_e32 v35, v46, v46
	v_fmac_f32_e32 v45, v40, v40
	v_fmac_f32_e32 v47, v42, v42
	v_fmac_f32_e32 v54, v36, v36
	v_fmac_f32_e32 v55, v38, v38
	v_fmac_f32_e32 v56, v52, v52
	v_fmac_f32_e32 v57, v50, v50
	v_add_f32_e32 v34, v34, v35
	v_add_f32_e32 v35, v45, v47
	v_add_f32_e32 v44, v54, v55
	v_add_f32_e32 v45, v56, v57
	v_add_f32_e32 v34, v34, v35
	v_add_f32_e32 v35, v44, v45
	v_add_f32_e32 v44, v34, v35
	ds_bpermute_b32 v45, v146, v44
	v_cvt_pk_bf16_f32 v34, v40, v41
	v_cvt_pk_bf16_f32 v35, v42, v43
	global_store_dwordx4 v[58:59], v[32:35], off
	s_waitcnt lgkmcnt(0)
	s_nop 0
	v_add_f32_e32 v32, v44, v45
	ds_bpermute_b32 v33, v145, v32
	v_cvt_pk_bf16_f32 v34, v36, v37
	v_cvt_pk_bf16_f32 v35, v38, v39
	v_cvt_pk_bf16_f32 v36, v52, v53
	v_cvt_pk_bf16_f32 v37, v50, v51
	global_store_dwordx4 v[58:59], v[34:37], off offset:256
	s_and_saveexec_b64 s[34:35], vcc
	s_cbranch_execz .LBB0_742
	s_waitcnt lgkmcnt(0)
	v_add_f32_e32 v34, v32, v33
	v_lshlrev_b64 v[32:33], 6, v[48:49]
	v_lshl_add_u64 v[32:33], s[18:19], 0, v[32:33]
	v_lshl_add_u64 v[32:33], s[26:27], 2, v[32:33]
	v_lshl_add_u64 v[32:33], s[24:25], 2, v[32:33]
	global_store_dword v[32:33], v34, off
; __device__ __forceinline__ u32x4 pack8(f32x4 a, f32x4 b) { u32x4 w; w.x = cvt_pk_bf16(a[0], a[1]); w.y = cvt_pk_bf16(a[2], a[3]); w.z = cvt_pk_bf16(b[0], b[1]); w.w = cvt_pk_bf16(b[2], b[3]); return w; }
;     __device__ __forceinline__ void operator()(const AccT& acc, const pg8::Unit& u, int wr, int wc, int fr, int fq) const {
;     ...
;                 const int row = u.pm * 256 + ai * 128 + wr * 64 + m * 16 + fr;
;                 const size_t off = (size_t)row * 1024 + u.pn * 256 + 32 * wc + 8 * fq;
;                 float ss = 0.f;
; #pragma unroll
;                 for (int bj = 0; bj < 2; ++bj) {
;                     const u32x4 bv = *(const u32x4*)(XB + off + 128 * bj);
;                     f32x4 b0, b1;
;                     b0[0] = __builtin_bit_cast(float, bv[0] << 16); b0[1] = __builtin_bit_cast(float, bv[0] & 0xffff0000u); b0[2] = __builtin_bit_cast(float, bv[1] << 16); b0[3] = __builtin_bit_cast(float, bv[1] & 0xffff0000u);
;                     b1[0] = __builtin_bit_cast(float, bv[2] << 16); b1[1] = __builtin_bit_cast(float, bv[2] & 0xffff0000u); b1[2] = __builtin_bit_cast(float, bv[3] << 16); b1[3] = __builtin_bit_cast(float, bv[3] & 0xffff0000u);
;                     const f32x4 o0 = b0 + acc[ai][bj][m][0], o1 = b1 + acc[ai][bj][m][1];
;                     if (LAST) { *(f32x4*)(out + off + 128 * bj) = o0; *(f32x4*)(out + off + 128 * bj + 4) = o1; }
;                     else {
;                         *(u32x4*)(XB + off + 128 * bj) = pack8(o0, o1);
;                         ss += ((o0[0] * o0[0] + o0[1] * o0[1]) + (o0[2] * o0[2] + o0[3] * o0[3])) + ((o1[0] * o1[0] + o1[1] * o1[1]) + (o1[2] * o1[2] + o1[3] * o1[3]));
;                     }
;                 }
;                 if (!LAST) {
;                     ss += __shfl_xor(ss, 16); ss += __shfl_xor(ss, 32);
;                     if (fq == 0) ssq_out[(size_t)row * 16 + u.pn * 4 + wc] = ss;
;                 }
.LBB0_742:
	s_or_b64 exec, exec, s[34:35]
	v_add_u32_e32 v32, 0xa0, v138
	s_waitcnt lgkmcnt(0)
	v_ashrrev_i32_e32 v33, 31, v32
	v_lshlrev_b64 v[34:35], 11, v[32:33]
	v_lshl_add_u64 v[34:35], s[16:17], 0, v[34:35]
	v_lshl_add_u64 v[34:35], s[28:29], 1, v[34:35]
	v_lshl_add_u64 v[34:35], s[30:31], 1, v[34:35]
	v_lshl_add_u64 v[42:43], v[34:35], 0, v[132:133]
	s_nop 1
	v_mov_b32_e32 v34, v214
	v_mov_b32_e32 v35, v215
	v_mov_b32_e32 v36, v216
	v_mov_b32_e32 v37, v217
	s_nop 1
	v_mov_b32_e32 v38, v222
	v_mov_b32_e32 v39, v223
	v_mov_b32_e32 v40, v224
	v_mov_b32_e32 v41, v225
	v_lshlrev_b32_e32 v44, 16, v34
	v_and_b32_e32 v45, 0xffff0000, v34
	v_lshlrev_b32_e32 v34, 16, v35
	v_and_b32_e32 v35, 0xffff0000, v35
	v_lshlrev_b32_e32 v46, 16, v36
	v_and_b32_e32 v47, 0xffff0000, v36
	v_lshlrev_b32_e32 v36, 16, v37
	v_and_b32_e32 v37, 0xffff0000, v37
	v_lshlrev_b32_e32 v48, 16, v38
	v_and_b32_e32 v49, 0xffff0000, v38
	v_lshlrev_b32_e32 v38, 16, v39
	v_and_b32_e32 v39, 0xffff0000, v39
	v_lshlrev_b32_e32 v50, 16, v40
	v_and_b32_e32 v51, 0xffff0000, v40
	v_lshlrev_b32_e32 v40, 16, v41
	v_and_b32_e32 v41, 0xffff0000, v41
	v_pk_add_f32 v[30:31], v[30:31], v[34:35]
	v_pk_add_f32 v[28:29], v[28:29], v[44:45]
	v_pk_add_f32 v[26:27], v[26:27], v[36:37]
	v_pk_add_f32 v[24:25], v[24:25], v[46:47]
	v_pk_add_f32 v[22:23], v[22:23], v[38:39]
	v_pk_add_f32 v[20:21], v[20:21], v[48:49]
	v_pk_add_f32 v[34:35], v[18:19], v[40:41]
	v_pk_add_f32 v[36:37], v[16:17], v[50:51]
	v_cvt_pk_bf16_f32 v16, v28, v29
	v_cvt_pk_bf16_f32 v17, v30, v31
	v_mul_f32_e32 v18, v29, v29
	v_mul_f32_e32 v19, v31, v31
	v_mul_f32_e32 v29, v25, v25
	v_mul_f32_e32 v31, v27, v27
	v_mul_f32_e32 v38, v21, v21
	v_mul_f32_e32 v39, v23, v23
	v_mul_f32_e32 v40, v37, v37
	v_mul_f32_e32 v41, v35, v35
	v_fmac_f32_e32 v18, v28, v28
	v_fmac_f32_e32 v19, v30, v30
	v_fmac_f32_e32 v29, v24, v24
	v_fmac_f32_e32 v31, v26, v26
	v_fmac_f32_e32 v38, v20, v20
	v_fmac_f32_e32 v39, v22, v22
	v_fmac_f32_e32 v40, v36, v36
	v_fmac_f32_e32 v41, v34, v34
	v_add_f32_e32 v18, v18, v19
	v_add_f32_e32 v19, v29, v31
	v_add_f32_e32 v28, v38, v39
	v_add_f32_e32 v29, v40, v41
	v_add_f32_e32 v18, v18, v19
	v_add_f32_e32 v19, v28, v29
	v_add_f32_e32 v28, v18, v19
	ds_bpermute_b32 v29, v146, v28
	v_cvt_pk_bf16_f32 v18, v24, v25
	v_cvt_pk_bf16_f32 v19, v26, v27
	global_store_dwordx4 v[42:43], v[16:19], off
	s_waitcnt lgkmcnt(0)
	s_nop 0
	v_add_f32_e32 v16, v28, v29
	ds_bpermute_b32 v17, v145, v16
	v_cvt_pk_bf16_f32 v18, v20, v21
	v_cvt_pk_bf16_f32 v19, v22, v23
	v_cvt_pk_bf16_f32 v20, v36, v37
	v_cvt_pk_bf16_f32 v21, v34, v35
	global_store_dwordx4 v[42:43], v[18:21], off offset:256
	s_and_saveexec_b64 s[34:35], vcc
	s_cbranch_execz .LBB0_744
	s_waitcnt lgkmcnt(0)
	v_add_f32_e32 v18, v16, v17
	v_lshlrev_b64 v[16:17], 6, v[32:33]
	v_lshl_add_u64 v[16:17], s[18:19], 0, v[16:17]
	v_lshl_add_u64 v[16:17], s[26:27], 2, v[16:17]
	v_lshl_add_u64 v[16:17], s[24:25], 2, v[16:17]
	global_store_dword v[16:17], v18, off
.LBB0_744:
	s_or_b64 exec, exec, s[34:35]
	v_add_u32_e32 v16, 0xb0, v138
	s_waitcnt lgkmcnt(0)
	v_ashrrev_i32_e32 v17, 31, v16
	v_lshlrev_b64 v[18:19], 11, v[16:17]
	v_lshl_add_u64 v[18:19], s[16:17], 0, v[18:19]
	v_lshl_add_u64 v[18:19], s[28:29], 1, v[18:19]
	v_lshl_add_u64 v[18:19], s[30:31], 1, v[18:19]
	v_lshl_add_u64 v[26:27], v[18:19], 0, v[132:133]
	s_nop 1
	v_mov_b32_e32 v18, v226
	v_mov_b32_e32 v19, v227
	v_mov_b32_e32 v20, v228
	v_mov_b32_e32 v21, v229
	s_nop 1
	v_mov_b32_e32 v22, v230
	v_mov_b32_e32 v23, v231
	v_mov_b32_e32 v24, v232
	v_mov_b32_e32 v25, v233
	v_lshlrev_b32_e32 v28, 16, v18
	v_and_b32_e32 v29, 0xffff0000, v18
	v_lshlrev_b32_e32 v18, 16, v19
	v_and_b32_e32 v19, 0xffff0000, v19
	v_lshlrev_b32_e32 v30, 16, v20
	v_and_b32_e32 v31, 0xffff0000, v20
	v_lshlrev_b32_e32 v20, 16, v21
	v_and_b32_e32 v21, 0xffff0000, v21
	v_lshlrev_b32_e32 v32, 16, v22
	v_and_b32_e32 v33, 0xffff0000, v22
	v_lshlrev_b32_e32 v22, 16, v23
	v_and_b32_e32 v23, 0xffff0000, v23
	v_lshlrev_b32_e32 v34, 16, v24
	v_and_b32_e32 v35, 0xffff0000, v24
	v_lshlrev_b32_e32 v24, 16, v25
	v_and_b32_e32 v25, 0xffff0000, v25
	v_pk_add_f32 v[14:15], v[14:15], v[18:19]
	v_pk_add_f32 v[12:13], v[12:13], v[28:29]
	v_pk_add_f32 v[10:11], v[10:11], v[20:21]
	v_pk_add_f32 v[8:9], v[8:9], v[30:31]
	v_pk_add_f32 v[6:7], v[6:7], v[22:23]
	v_pk_add_f32 v[4:5], v[4:5], v[32:33]
	v_pk_add_f32 v[18:19], v[2:3], v[24:25]
	v_pk_add_f32 v[20:21], v[0:1], v[34:35]
	v_cvt_pk_bf16_f32 v0, v12, v13
	v_cvt_pk_bf16_f32 v1, v14, v15
	v_mul_f32_e32 v2, v13, v13
	v_mul_f32_e32 v3, v15, v15
	v_mul_f32_e32 v13, v9, v9
	v_mul_f32_e32 v15, v11, v11
	v_mul_f32_e32 v22, v5, v5
	v_mul_f32_e32 v23, v7, v7
	v_mul_f32_e32 v24, v21, v21
	v_mul_f32_e32 v25, v19, v19
	v_fmac_f32_e32 v2, v12, v12
	v_fmac_f32_e32 v3, v14, v14
	v_fmac_f32_e32 v13, v8, v8
	v_fmac_f32_e32 v15, v10, v10
	v_fmac_f32_e32 v22, v4, v4
	v_fmac_f32_e32 v23, v6, v6
	v_fmac_f32_e32 v24, v20, v20
	v_fmac_f32_e32 v25, v18, v18
	v_add_f32_e32 v2, v2, v3
	v_add_f32_e32 v3, v13, v15
	v_add_f32_e32 v12, v22, v23
	v_add_f32_e32 v13, v24, v25
	v_add_f32_e32 v2, v2, v3
	v_add_f32_e32 v3, v12, v13
	v_add_f32_e32 v12, v2, v3
	ds_bpermute_b32 v13, v146, v12
	v_cvt_pk_bf16_f32 v2, v8, v9
	v_cvt_pk_bf16_f32 v3, v10, v11
	global_store_dwordx4 v[26:27], v[0:3], off
	s_waitcnt lgkmcnt(0)
	s_nop 0
	v_add_f32_e32 v0, v12, v13
	ds_bpermute_b32 v1, v145, v0
	v_cvt_pk_bf16_f32 v2, v4, v5
	v_cvt_pk_bf16_f32 v3, v6, v7
	v_cvt_pk_bf16_f32 v4, v20, v21
	v_cvt_pk_bf16_f32 v5, v18, v19
	global_store_dwordx4 v[26:27], v[2:5], off offset:256
	s_and_saveexec_b64 s[28:29], vcc
	s_cbranch_execz .LBB0_746
	s_waitcnt lgkmcnt(0)
	v_add_f32_e32 v2, v0, v1
	v_lshlrev_b64 v[0:1], 6, v[16:17]
	v_lshl_add_u64 v[0:1], s[18:19], 0, v[0:1]
	v_lshl_add_u64 v[0:1], s[26:27], 2, v[0:1]
	v_lshl_add_u64 v[0:1], s[24:25], 2, v[0:1]
	global_store_dword v[0:1], v2, off

; __device__ __forceinline__ u32x4 pack8(f32x4 a, f32x4 b) { u32x4 w; w.x = cvt_pk_bf16(a[0], a[1]); w.y = cvt_pk_bf16(a[2], a[3]); w.z = cvt_pk_bf16(b[0], b[1]); w.w = cvt_pk_bf16(b[2], b[3]); return w; }
;     __device__ __forceinline__ void operator()(const AccT& acc, const pg8::Unit& u, int wr, int wc, int fr, int fq) const {
;     ...
;                 const int row = u.pm * 256 + ai * 128 + wr * 64 + m * 16 + fr;
;                 const size_t off = (size_t)row * 1024 + u.pn * 256 + 32 * wc + 8 * fq;
;                 float ss = 0.f;
; #pragma unroll
;                 for (int bj = 0; bj < 2; ++bj) {
;                     const u32x4 bv = *(const u32x4*)(XB + off + 128 * bj);
;                     f32x4 b0, b1;
;                     b0[0] = __builtin_bit_cast(float, bv[0] << 16); b0[1] = __builtin_bit_cast(float, bv[0] & 0xffff0000u); b0[2] = __builtin_bit_cast(float, bv[1] << 16); b0[3] = __builtin_bit_cast(float, bv[1] & 0xffff0000u);
;                     b1[0] = __builtin_bit_cast(float, bv[2] << 16); b1[1] = __builtin_bit_cast(float, bv[2] & 0xffff0000u); b1[2] = __builtin_bit_cast(float, bv[3] << 16); b1[3] = __builtin_bit_cast(float, bv[3] & 0xffff0000u);
;                     const f32x4 o0 = b0 + acc[ai][bj][m][0], o1 = b1 + acc[ai][bj][m][1];
;                     if (LAST) { *(f32x4*)(out + off + 128 * bj) = o0; *(f32x4*)(out + off + 128 * bj + 4) = o1; }
;                     else {
;                         *(u32x4*)(XB + off + 128 * bj) = pack8(o0, o1);
;                         ss += ((o0[0] * o0[0] + o0[1] * o0[1]) + (o0[2] * o0[2] + o0[3] * o0[3])) + ((o1[0] * o1[0] + o1[1] * o1[1]) + (o1[2] * o1[2] + o1[3] * o1[3]));
;                     }
;                 }
;                 if (!LAST) {
;                     ss += __shfl_xor(ss, 16); ss += __shfl_xor(ss, 32);
;                     if (fq == 0) ssq_out[(size_t)row * 16 + u.pn * 4 + wc] = ss;
;                 }
.LBB0_1184:
	s_mov_b32 s21, s44
	v_mov_b32_e32 v136, v220
	s_mov_b32 s34, s51
	s_lshl_b32 s23, s30, 8
	s_lshl_b32 s21, s21, 6
	s_add_i32 s21, s21, s23
	v_and_or_b32 v146, v136, 15, s21
	v_ashrrev_i32_e32 v147, 31, v146
	s_lshl_b32 s30, s28, 8
	v_lshlrev_b64 v[156:157], 11, v[146:147]
	s_ashr_i32 s31, s30, 31
	s_lshl_b32 s36, s34, 5
	v_lshl_add_u64 v[156:157], s[12:13], 0, v[156:157]
	v_bfe_u32 v155, v136, 4, 2
	s_ashr_i32 s37, s36, 31
	v_lshl_add_u64 v[156:157], s[30:31], 1, v[156:157]
	v_lshl_add_u64 v[156:157], s[36:37], 1, v[156:157]
	v_lshlrev_b32_e32 v136, 4, v155
	v_lshl_add_u64 v[164:165], v[156:157], 0, v[136:137]
	s_mov_b32 s88, 0x8000
	s_mov_b32 s89, 0
	s_mov_b32 s90, 0x28000
	s_mov_b32 s91, 0
	global_load_dwordx4 v[174:177], v[164:165], off
	global_load_dwordx4 v[178:181], v[164:165], off offset:256
	v_lshl_add_u64 v[244:245], v[164:165], 0, s[88:89]
	global_load_dwordx4 v[182:185], v[244:245], off
	global_load_dwordx4 v[186:189], v[244:245], off offset:256
	v_lshl_add_u64 v[244:245], v[244:245], 0, s[88:89]
	global_load_dwordx4 v[190:193], v[244:245], off
	global_load_dwordx4 v[194:197], v[244:245], off offset:256
	v_lshl_add_u64 v[244:245], v[244:245], 0, s[88:89]
	global_load_dwordx4 v[198:201], v[244:245], off
	global_load_dwordx4 v[202:205], v[244:245], off offset:256
	v_lshl_add_u64 v[244:245], v[244:245], 0, s[90:91]
	global_load_dwordx4 v[206:209], v[244:245], off
	global_load_dwordx4 v[210:213], v[244:245], off offset:256
	v_lshl_add_u64 v[244:245], v[244:245], 0, s[88:89]
	global_load_dwordx4 v[214:217], v[244:245], off
	global_load_dwordx4 v[224:227], v[244:245], off offset:256
	v_lshl_add_u64 v[244:245], v[244:245], 0, s[88:89]
	global_load_dwordx4 v[228:231], v[244:245], off
	global_load_dwordx4 v[232:235], v[244:245], off offset:256
	v_lshl_add_u64 v[244:245], v[244:245], 0, s[88:89]
	global_load_dwordx4 v[236:239], v[244:245], off
	global_load_dwordx4 v[240:243], v[244:245], off offset:256
	s_waitcnt vmcnt(0)
	s_nop 1
	v_mov_b32_e32 v156, v174
	v_mov_b32_e32 v157, v175
	v_mov_b32_e32 v158, v176
	v_mov_b32_e32 v159, v177
	s_nop 1
	v_mov_b32_e32 v160, v178
	v_mov_b32_e32 v161, v179
	v_mov_b32_e32 v162, v180
	v_mov_b32_e32 v163, v181
	v_and_b32_e32 v153, 64, v152
	v_xor_b32_e32 v136, 16, v152
	v_add_u32_e32 v153, 64, v153
	v_xor_b32_e32 v154, 32, v152
	v_cmp_lt_i32_e32 vcc, v136, v153
	s_lshl_b32 s28, s28, 2
	s_ashr_i32 s29, s28, 31
	v_cndmask_b32_e32 v136, v152, v136, vcc
	v_cmp_lt_i32_e32 vcc, v154, v153
	s_ashr_i32 s35, s34, 31
	v_lshlrev_b32_e32 v166, 16, v156
	v_and_b32_e32 v167, 0xffff0000, v156
	v_lshlrev_b32_e32 v156, 16, v157
	v_and_b32_e32 v157, 0xffff0000, v157
	v_lshlrev_b32_e32 v168, 16, v158
	v_and_b32_e32 v169, 0xffff0000, v158
	v_lshlrev_b32_e32 v158, 16, v159
	v_and_b32_e32 v159, 0xffff0000, v159
	v_lshlrev_b32_e32 v170, 16, v160
	v_and_b32_e32 v171, 0xffff0000, v160
	v_lshlrev_b32_e32 v160, 16, v161
	v_and_b32_e32 v161, 0xffff0000, v161
	v_lshlrev_b32_e32 v172, 16, v162
	v_and_b32_e32 v173, 0xffff0000, v162
	v_lshlrev_b32_e32 v162, 16, v163
	v_and_b32_e32 v163, 0xffff0000, v163
	v_pk_add_f32 v[126:127], v[126:127], v[156:157]
	v_pk_add_f32 v[124:125], v[124:125], v[166:167]
	v_pk_add_f32 v[122:123], v[122:123], v[158:159]
	v_pk_add_f32 v[120:121], v[120:121], v[168:169]
	v_pk_add_f32 v[118:119], v[118:119], v[160:161]
	v_pk_add_f32 v[116:117], v[116:117], v[170:171]
	v_pk_add_f32 v[156:157], v[114:115], v[162:163]
	v_pk_add_f32 v[158:159], v[112:113], v[172:173]
	v_cndmask_b32_e32 v153, v152, v154, vcc
	v_lshlrev_b32_e32 v154, 2, v136
	v_cvt_pk_bf16_f32 v112, v124, v125
	v_cvt_pk_bf16_f32 v113, v126, v127
	v_mul_f32_e32 v114, v125, v125
	v_mul_f32_e32 v115, v127, v127
	v_mul_f32_e32 v125, v121, v121
	v_mul_f32_e32 v127, v123, v123
	v_mul_f32_e32 v136, v117, v117
	v_mul_f32_e32 v160, v119, v119
	v_mul_f32_e32 v161, v159, v159
	v_mul_f32_e32 v162, v157, v157
	v_fmac_f32_e32 v114, v124, v124
	v_fmac_f32_e32 v115, v126, v126
	v_fmac_f32_e32 v125, v120, v120
	v_fmac_f32_e32 v127, v122, v122
	v_fmac_f32_e32 v136, v116, v116
	v_fmac_f32_e32 v160, v118, v118
	v_fmac_f32_e32 v161, v158, v158
	v_fmac_f32_e32 v162, v156, v156
	v_add_f32_e32 v114, v114, v115
	v_add_f32_e32 v115, v125, v127
	v_add_f32_e32 v124, v136, v160
	v_add_f32_e32 v125, v161, v162
	v_add_f32_e32 v114, v114, v115
	v_add_f32_e32 v115, v124, v125
	v_add_f32_e32 v124, v114, v115
	ds_bpermute_b32 v125, v154, v124
	v_cvt_pk_bf16_f32 v114, v120, v121
	v_cvt_pk_bf16_f32 v115, v122, v123
	v_lshlrev_b32_e32 v153, 2, v153
	global_store_dwordx4 v[164:165], v[112:115], off
	v_cmp_eq_u32_e32 vcc, 0, v155
	s_waitcnt lgkmcnt(0)
	v_add_f32_e32 v112, v124, v125
	ds_bpermute_b32 v113, v153, v112
	v_cvt_pk_bf16_f32 v114, v116, v117
	v_cvt_pk_bf16_f32 v115, v118, v119
	v_cvt_pk_bf16_f32 v116, v158, v159
	v_cvt_pk_bf16_f32 v117, v156, v157
	global_store_dwordx4 v[164:165], v[114:117], off offset:256
	s_and_saveexec_b64 s[38:39], vcc
	s_cbranch_execz .LBB0_1186
	s_waitcnt lgkmcnt(0)
	v_add_f32_e32 v114, v112, v113
	v_lshlrev_b64 v[112:113], 6, v[146:147]
	v_lshl_add_u64 v[112:113], s[14:15], 0, v[112:113]
	v_lshl_add_u64 v[112:113], s[28:29], 2, v[112:113]
	v_lshl_add_u64 v[112:113], s[34:35], 2, v[112:113]
	global_store_dword v[112:113], v114, off

;     __device__ __forceinline__ void operator()(const AccT& acc, const pg8::Unit& u, int wr, int wc, int fr, int fq) const {
;     ...
;                 const int row = u.pm * 256 + ai * 128 + wr * 64 + m * 16 + fr;
;                 const size_t off = (size_t)row * 1024 + u.pn * 256 + 32 * wc + 8 * fq;
;                 float ss = 0.f;
; #pragma unroll
;                 for (int bj = 0; bj < 2; ++bj) {
;                     const u32x4 bv = *(const u32x4*)(XB + off + 128 * bj);
;                     f32x4 b0, b1;
;                     b0[0] = __builtin_bit_cast(float, bv[0] << 16); b0[1] = __builtin_bit_cast(float, bv[0] & 0xffff0000u); b0[2] = __builtin_bit_cast(float, bv[1] << 16); b0[3] = __builtin_bit_cast(float, bv[1] & 0xffff0000u);
;                     b1[0] = __builtin_bit_cast(float, bv[2] << 16); b1[1] = __builtin_bit_cast(float, bv[2] & 0xffff0000u); b1[2] = __builtin_bit_cast(float, bv[3] << 16); b1[3] = __builtin_bit_cast(float, bv[3] & 0xffff0000u);
;                     const f32x4 o0 = b0 + acc[ai][bj][m][0], o1 = b1 + acc[ai][bj][m][1];
;                     if (LAST) { *(f32x4*)(out + off + 128 * bj) = o0; *(f32x4*)(out + off + 128 * bj + 4) = o1; }
.LBB0_1410:
	s_mov_b32 s16, s28
	v_mov_b32_e32 v137, v220
	s_mov_b32 s17, s36
	s_lshl_b32 s18, s43, 8
	s_lshl_b32 s16, s16, 6
	s_add_i32 s16, s16, s18
	v_and_or_b32 v136, v137, 15, s16
	s_lshl_b32 s16, s44, 8
	s_lshl_b32 s17, s17, 5
	s_ashr_i32 s18, s16, 31
	s_ashr_i32 s19, s17, 31
	s_add_u32 s16, s17, s16
	v_lshrrev_b32_e32 v137, 1, v137
	s_addc_u32 s17, s19, s18
	v_and_or_b32 v138, v137, 24, s16
	v_ashrrev_i32_e32 v137, 31, v136
	v_mov_b32_e32 v139, s17
	v_lshlrev_b64 v[144:145], 10, v[136:137]
	v_lshl_add_u64 v[148:149], v[144:145], 0, v[138:139]
	v_lshl_add_u64 v[150:151], v[148:149], 1, s[10:11]
	s_mov_b32 s88, 0x8000
	s_mov_b32 s89, 0
	s_mov_b32 s90, 0x28000
	s_mov_b32 s91, 0
	global_load_dwordx4 v[156:159], v[150:151], off
	global_load_dwordx4 v[160:163], v[150:151], off offset:256
	v_lshl_add_u64 v[226:227], v[150:151], 0, s[88:89]
	global_load_dwordx4 v[164:167], v[226:227], off
	global_load_dwordx4 v[168:171], v[226:227], off offset:256
	v_lshl_add_u64 v[226:227], v[226:227], 0, s[88:89]
	global_load_dwordx4 v[172:175], v[226:227], off
	global_load_dwordx4 v[176:179], v[226:227], off offset:256
	v_lshl_add_u64 v[226:227], v[226:227], 0, s[88:89]
	global_load_dwordx4 v[180:183], v[226:227], off
	global_load_dwordx4 v[184:187], v[226:227], off offset:256
	v_lshl_add_u64 v[226:227], v[226:227], 0, s[90:91]
	global_load_dwordx4 v[188:191], v[226:227], off
	global_load_dwordx4 v[192:195], v[226:227], off offset:256
	v_lshl_add_u64 v[226:227], v[226:227], 0, s[88:89]
	global_load_dwordx4 v[196:199], v[226:227], off
	global_load_dwordx4 v[200:203], v[226:227], off offset:256
	v_lshl_add_u64 v[226:227], v[226:227], 0, s[88:89]
	global_load_dwordx4 v[206:209], v[226:227], off
	global_load_dwordx4 v[210:213], v[226:227], off offset:256
	v_lshl_add_u64 v[226:227], v[226:227], 0, s[88:89]
	global_load_dwordx4 v[214:217], v[226:227], off
	global_load_dwordx4 v[222:225], v[226:227], off offset:256
	s_waitcnt vmcnt(0)
	s_nop 1
	v_mov_b32_e32 v144, v156
	v_mov_b32_e32 v145, v157
	v_mov_b32_e32 v146, v158
	v_mov_b32_e32 v147, v159
	v_lshl_add_u64 v[148:149], v[148:149], 2, s[78:79]
	s_and_b64 vcc, exec, s[0:1]
	s_mov_b64 s[0:1], -1
	v_lshlrev_b32_e32 v152, 16, v144
	v_and_b32_e32 v153, 0xffff0000, v144
	v_lshlrev_b32_e32 v144, 16, v145
	v_and_b32_e32 v145, 0xffff0000, v145
	v_lshlrev_b32_e32 v154, 16, v146
	v_and_b32_e32 v155, 0xffff0000, v146
	v_lshlrev_b32_e32 v146, 16, v147
	v_and_b32_e32 v147, 0xffff0000, v147
	v_pk_add_f32 v[126:127], v[126:127], v[144:145]
	v_pk_add_f32 v[124:125], v[124:125], v[152:153]
	v_pk_add_f32 v[122:123], v[122:123], v[146:147]
	v_pk_add_f32 v[120:121], v[120:121], v[154:155]
	global_store_dwordx4 v[148:149], v[124:127], off
	global_store_dwordx4 v[148:149], v[120:123], off offset:16
	s_nop 1
	v_mov_b32_e32 v120, v160
	v_mov_b32_e32 v121, v161
	v_mov_b32_e32 v122, v162
	v_mov_b32_e32 v123, v163
	v_or_b32_e32 v124, 16, v136
	v_ashrrev_i32_e32 v125, 31, v124
	v_lshlrev_b64 v[124:125], 10, v[124:125]
	v_lshl_add_u64 v[124:125], v[124:125], 0, v[138:139]
	v_lshl_add_u64 v[126:127], v[124:125], 1, s[10:11]
	v_lshlrev_b32_e32 v144, 16, v120
	v_and_b32_e32 v145, 0xffff0000, v120
	v_lshlrev_b32_e32 v120, 16, v121
	v_and_b32_e32 v121, 0xffff0000, v121
	v_lshlrev_b32_e32 v146, 16, v122
	v_and_b32_e32 v147, 0xffff0000, v122
	v_lshlrev_b32_e32 v122, 16, v123
	v_and_b32_e32 v123, 0xffff0000, v123
	v_pk_add_f32 v[118:119], v[118:119], v[120:121]
	v_pk_add_f32 v[116:117], v[116:117], v[144:145]
	v_pk_add_f32 v[114:115], v[114:115], v[122:123]
	v_pk_add_f32 v[112:113], v[112:113], v[146:147]
	global_store_dwordx4 v[148:149], v[116:119], off offset:512
	global_store_dwordx4 v[148:149], v[112:115], off offset:528
	s_nop 1
	v_mov_b32_e32 v112, v164
	v_mov_b32_e32 v113, v165
	v_mov_b32_e32 v114, v166
	v_mov_b32_e32 v115, v167
	v_lshl_add_u64 v[116:117], v[124:125], 2, s[78:79]
	v_lshlrev_b32_e32 v118, 16, v112
	v_and_b32_e32 v119, 0xffff0000, v112
	v_lshlrev_b32_e32 v112, 16, v113
	v_and_b32_e32 v113, 0xffff0000, v113
	v_lshlrev_b32_e32 v120, 16, v114
	v_and_b32_e32 v121, 0xffff0000, v114
	v_lshlrev_b32_e32 v114, 16, v115
	v_and_b32_e32 v115, 0xffff0000, v115
	v_pk_add_f32 v[110:111], v[110:111], v[112:113]
	v_pk_add_f32 v[108:109], v[108:109], v[118:119]
	v_pk_add_f32 v[106:107], v[106:107], v[114:115]
	v_pk_add_f32 v[104:105], v[104:105], v[120:121]
	global_store_dwordx4 v[116:117], v[108:111], off
	global_store_dwordx4 v[116:117], v[104:107], off offset:16
	s_nop 1
	v_mov_b32_e32 v104, v168
	v_mov_b32_e32 v105, v169
	v_mov_b32_e32 v106, v170
	v_mov_b32_e32 v107, v171
	v_or_b32_e32 v108, 32, v136
	v_ashrrev_i32_e32 v109, 31, v108
	v_lshlrev_b64 v[108:109], 10, v[108:109]
	v_lshl_add_u64 v[108:109], v[108:109], 0, v[138:139]
	v_lshl_add_u64 v[110:111], v[108:109], 1, s[10:11]
	v_lshlrev_b32_e32 v112, 16, v104
	v_and_b32_e32 v113, 0xffff0000, v104
	v_lshlrev_b32_e32 v104, 16, v105
	v_and_b32_e32 v105, 0xffff0000, v105
	v_lshlrev_b32_e32 v114, 16, v106
	v_and_b32_e32 v115, 0xffff0000, v106
	v_lshlrev_b32_e32 v106, 16, v107
	v_and_b32_e32 v107, 0xffff0000, v107
	v_pk_add_f32 v[102:103], v[102:103], v[104:105]
	v_pk_add_f32 v[100:101], v[100:101], v[112:113]
	v_pk_add_f32 v[98:99], v[98:99], v[106:107]
	v_pk_add_f32 v[96:97], v[96:97], v[114:115]
	global_store_dwordx4 v[116:117], v[100:103], off offset:512
	global_store_dwordx4 v[116:117], v[96:99], off offset:528
	s_nop 1
	v_mov_b32_e32 v96, v172
	v_mov_b32_e32 v97, v173
	v_mov_b32_e32 v98, v174
	v_mov_b32_e32 v99, v175
	v_lshl_add_u64 v[100:101], v[108:109], 2, s[78:79]
	v_lshlrev_b32_e32 v102, 16, v96
	v_and_b32_e32 v103, 0xffff0000, v96
	v_lshlrev_b32_e32 v96, 16, v97
;     __device__ __forceinline__ void operator()(const AccT& acc, const pg8::Unit& u, int wr, int wc, int fr, int fq) const {
;     ...
;                 const int row = u.pm * 256 + ai * 128 + wr * 64 + m * 16 + fr;
;                 const size_t off = (size_t)row * 1024 + u.pn * 256 + 32 * wc + 8 * fq;
;                 float ss = 0.f;
; #pragma unroll
;                 for (int bj = 0; bj < 2; ++bj) {
;                     const u32x4 bv = *(const u32x4*)(XB + off + 128 * bj);
;                     f32x4 b0, b1;
;                     b0[0] = __builtin_bit_cast(float, bv[0] << 16); b0[1] = __builtin_bit_cast(float, bv[0] & 0xffff0000u); b0[2] = __builtin_bit_cast(float, bv[1] << 16); b0[3] = __builtin_bit_cast(float, bv[1] & 0xffff0000u);
;                     b1[0] = __builtin_bit_cast(float, bv[2] << 16); b1[1] = __builtin_bit_cast(float, bv[2] & 0xffff0000u); b1[2] = __builtin_bit_cast(float, bv[3] << 16); b1[3] = __builtin_bit_cast(float, bv[3] & 0xffff0000u);
;                     const f32x4 o0 = b0 + acc[ai][bj][m][0], o1 = b1 + acc[ai][bj][m][1];
;                     if (LAST) { *(f32x4*)(out + off + 128 * bj) = o0; *(f32x4*)(out + off + 128 * bj + 4) = o1; }
	v_and_b32_e32 v97, 0xffff0000, v97
	v_lshlrev_b32_e32 v104, 16, v98
	v_and_b32_e32 v105, 0xffff0000, v98
	v_lshlrev_b32_e32 v98, 16, v99
	v_and_b32_e32 v99, 0xffff0000, v99
	v_pk_add_f32 v[94:95], v[94:95], v[96:97]
	v_pk_add_f32 v[92:93], v[92:93], v[102:103]
	v_pk_add_f32 v[90:91], v[90:91], v[98:99]
	v_pk_add_f32 v[88:89], v[88:89], v[104:105]
	global_store_dwordx4 v[100:101], v[92:95], off
	global_store_dwordx4 v[100:101], v[88:91], off offset:16
	s_nop 1
	v_mov_b32_e32 v88, v176
	v_mov_b32_e32 v89, v177
	v_mov_b32_e32 v90, v178
	v_mov_b32_e32 v91, v179
	v_or_b32_e32 v92, 48, v136
	v_ashrrev_i32_e32 v93, 31, v92
	v_lshlrev_b64 v[92:93], 10, v[92:93]
	v_lshl_add_u64 v[92:93], v[92:93], 0, v[138:139]
	v_lshl_add_u64 v[94:95], v[92:93], 1, s[10:11]
	v_lshlrev_b32_e32 v96, 16, v88
	v_and_b32_e32 v97, 0xffff0000, v88
	v_lshlrev_b32_e32 v88, 16, v89
	v_and_b32_e32 v89, 0xffff0000, v89
	v_lshlrev_b32_e32 v98, 16, v90
	v_and_b32_e32 v99, 0xffff0000, v90
	v_lshlrev_b32_e32 v90, 16, v91
	v_and_b32_e32 v91, 0xffff0000, v91
	v_pk_add_f32 v[86:87], v[86:87], v[88:89]
	v_pk_add_f32 v[84:85], v[84:85], v[96:97]
	v_pk_add_f32 v[82:83], v[82:83], v[90:91]
	v_pk_add_f32 v[80:81], v[80:81], v[98:99]
	global_store_dwordx4 v[100:101], v[84:87], off offset:512
	global_store_dwordx4 v[100:101], v[80:83], off offset:528
	s_nop 1
	v_mov_b32_e32 v80, v180
	v_mov_b32_e32 v81, v181
	v_mov_b32_e32 v82, v182
	v_mov_b32_e32 v83, v183
	v_lshl_add_u64 v[84:85], v[92:93], 2, s[78:79]
	v_lshlrev_b32_e32 v86, 16, v80
	v_and_b32_e32 v87, 0xffff0000, v80
	v_lshlrev_b32_e32 v80, 16, v81
	v_and_b32_e32 v81, 0xffff0000, v81
	v_lshlrev_b32_e32 v88, 16, v82
	v_and_b32_e32 v89, 0xffff0000, v82
	v_lshlrev_b32_e32 v82, 16, v83
	v_and_b32_e32 v83, 0xffff0000, v83
	v_pk_add_f32 v[78:79], v[78:79], v[80:81]
	v_pk_add_f32 v[76:77], v[76:77], v[86:87]
	v_pk_add_f32 v[74:75], v[74:75], v[82:83]
	v_pk_add_f32 v[72:73], v[72:73], v[88:89]
	global_store_dwordx4 v[84:85], v[76:79], off
	global_store_dwordx4 v[84:85], v[72:75], off offset:16
	s_nop 1
	v_mov_b32_e32 v72, v184
	v_mov_b32_e32 v73, v185
	v_mov_b32_e32 v74, v186
	v_mov_b32_e32 v75, v187
	v_add_u32_e32 v76, 0x80, v136
	v_ashrrev_i32_e32 v77, 31, v76
	v_lshlrev_b64 v[76:77], 10, v[76:77]
	v_lshl_add_u64 v[76:77], v[76:77], 0, v[138:139]
	v_lshl_add_u64 v[78:79], v[76:77], 1, s[10:11]
	v_lshlrev_b32_e32 v80, 16, v72
	v_and_b32_e32 v81, 0xffff0000, v72
	v_lshlrev_b32_e32 v72, 16, v73
	v_and_b32_e32 v73, 0xffff0000, v73
	v_lshlrev_b32_e32 v82, 16, v74
	v_and_b32_e32 v83, 0xffff0000, v74
	v_lshlrev_b32_e32 v74, 16, v75
	v_and_b32_e32 v75, 0xffff0000, v75
	v_pk_add_f32 v[70:71], v[70:71], v[72:73]
	v_pk_add_f32 v[68:69], v[68:69], v[80:81]
	v_pk_add_f32 v[66:67], v[66:67], v[74:75]
	v_pk_add_f32 v[64:65], v[64:65], v[82:83]
	global_store_dwordx4 v[84:85], v[68:71], off offset:512
	global_store_dwordx4 v[84:85], v[64:67], off offset:528
	s_nop 1
	v_mov_b32_e32 v64, v188
	v_mov_b32_e32 v65, v189
	v_mov_b32_e32 v66, v190
	v_mov_b32_e32 v67, v191
	v_lshl_add_u64 v[68:69], v[76:77], 2, s[78:79]
	v_lshlrev_b32_e32 v70, 16, v64
	v_and_b32_e32 v71, 0xffff0000, v64
	v_lshlrev_b32_e32 v64, 16, v65
	v_and_b32_e32 v65, 0xffff0000, v65
	v_lshlrev_b32_e32 v72, 16, v66
	v_and_b32_e32 v73, 0xffff0000, v66
	v_lshlrev_b32_e32 v66, 16, v67
	v_and_b32_e32 v67, 0xffff0000, v67
	v_pk_add_f32 v[62:63], v[62:63], v[64:65]
	v_pk_add_f32 v[60:61], v[60:61], v[70:71]
	v_pk_add_f32 v[58:59], v[58:59], v[66:67]
	v_pk_add_f32 v[56:57], v[56:57], v[72:73]
	global_store_dwordx4 v[68:69], v[60:63], off
	global_store_dwordx4 v[68:69], v[56:59], off offset:16
	s_nop 1
	v_mov_b32_e32 v56, v192
	v_mov_b32_e32 v57, v193
	v_mov_b32_e32 v58, v194
	v_mov_b32_e32 v59, v195
	v_add_u32_e32 v60, 0x90, v136
	v_ashrrev_i32_e32 v61, 31, v60
	v_lshlrev_b64 v[60:61], 10, v[60:61]
	v_lshl_add_u64 v[60:61], v[60:61], 0, v[138:139]
	v_lshl_add_u64 v[62:63], v[60:61], 1, s[10:11]
	v_lshlrev_b32_e32 v64, 16, v56
	v_and_b32_e32 v65, 0xffff0000, v56
	v_lshlrev_b32_e32 v56, 16, v57
	v_and_b32_e32 v57, 0xffff0000, v57
	v_lshlrev_b32_e32 v66, 16, v58
	v_and_b32_e32 v67, 0xffff0000, v58
	v_lshlrev_b32_e32 v58, 16, v59
	v_and_b32_e32 v59, 0xffff0000, v59
	v_pk_add_f32 v[54:55], v[54:55], v[56:57]
	v_pk_add_f32 v[52:53], v[52:53], v[64:65]
	v_pk_add_f32 v[50:51], v[50:51], v[58:59]
	v_pk_add_f32 v[48:49], v[48:49], v[66:67]
	global_store_dwordx4 v[68:69], v[52:55], off offset:512
	global_store_dwordx4 v[68:69], v[48:51], off offset:528
	s_nop 1
	v_mov_b32_e32 v48, v196
	v_mov_b32_e32 v49, v197
;     __device__ __forceinline__ void operator()(const AccT& acc, const pg8::Unit& u, int wr, int wc, int fr, int fq) const {
;     ...
;                 const int row = u.pm * 256 + ai * 128 + wr * 64 + m * 16 + fr;
;                 const size_t off = (size_t)row * 1024 + u.pn * 256 + 32 * wc + 8 * fq;
;                 float ss = 0.f;
; #pragma unroll
;                 for (int bj = 0; bj < 2; ++bj) {
;                     const u32x4 bv = *(const u32x4*)(XB + off + 128 * bj);
;                     f32x4 b0, b1;
;                     b0[0] = __builtin_bit_cast(float, bv[0] << 16); b0[1] = __builtin_bit_cast(float, bv[0] & 0xffff0000u); b0[2] = __builtin_bit_cast(float, bv[1] << 16); b0[3] = __builtin_bit_cast(float, bv[1] & 0xffff0000u);
;                     b1[0] = __builtin_bit_cast(float, bv[2] << 16); b1[1] = __builtin_bit_cast(float, bv[2] & 0xffff0000u); b1[2] = __builtin_bit_cast(float, bv[3] << 16); b1[3] = __builtin_bit_cast(float, bv[3] & 0xffff0000u);
;                     const f32x4 o0 = b0 + acc[ai][bj][m][0], o1 = b1 + acc[ai][bj][m][1];
;                     if (LAST) { *(f32x4*)(out + off + 128 * bj) = o0; *(f32x4*)(out + off + 128 * bj + 4) = o1; }
	v_mov_b32_e32 v50, v198
	v_mov_b32_e32 v51, v199
	v_lshl_add_u64 v[52:53], v[60:61], 2, s[78:79]
	v_lshlrev_b32_e32 v54, 16, v48
	v_and_b32_e32 v55, 0xffff0000, v48
	v_lshlrev_b32_e32 v48, 16, v49
	v_and_b32_e32 v49, 0xffff0000, v49
	v_lshlrev_b32_e32 v56, 16, v50
	v_and_b32_e32 v57, 0xffff0000, v50
	v_lshlrev_b32_e32 v50, 16, v51
	v_and_b32_e32 v51, 0xffff0000, v51
	v_pk_add_f32 v[46:47], v[46:47], v[48:49]
	v_pk_add_f32 v[44:45], v[44:45], v[54:55]
	v_pk_add_f32 v[42:43], v[42:43], v[50:51]
	v_pk_add_f32 v[40:41], v[40:41], v[56:57]
	global_store_dwordx4 v[52:53], v[44:47], off
	global_store_dwordx4 v[52:53], v[40:43], off offset:16
	s_nop 1
	v_mov_b32_e32 v40, v200
	v_mov_b32_e32 v41, v201
	v_mov_b32_e32 v42, v202
	v_mov_b32_e32 v43, v203
	v_add_u32_e32 v44, 0xa0, v136
	v_ashrrev_i32_e32 v45, 31, v44
	v_lshlrev_b64 v[44:45], 10, v[44:45]
	v_lshl_add_u64 v[44:45], v[44:45], 0, v[138:139]
	v_lshl_add_u64 v[46:47], v[44:45], 1, s[10:11]
	v_lshlrev_b32_e32 v48, 16, v40
	v_and_b32_e32 v49, 0xffff0000, v40
	v_lshlrev_b32_e32 v40, 16, v41
	v_and_b32_e32 v41, 0xffff0000, v41
	v_lshlrev_b32_e32 v50, 16, v42
	v_and_b32_e32 v51, 0xffff0000, v42
	v_lshlrev_b32_e32 v42, 16, v43
	v_and_b32_e32 v43, 0xffff0000, v43
	v_pk_add_f32 v[38:39], v[38:39], v[40:41]
	v_pk_add_f32 v[36:37], v[36:37], v[48:49]
	v_pk_add_f32 v[34:35], v[34:35], v[42:43]
	v_pk_add_f32 v[32:33], v[32:33], v[50:51]
	global_store_dwordx4 v[52:53], v[36:39], off offset:512
	global_store_dwordx4 v[52:53], v[32:35], off offset:528
	s_nop 1
	v_mov_b32_e32 v32, v206
	v_mov_b32_e32 v33, v207
	v_mov_b32_e32 v34, v208
	v_mov_b32_e32 v35, v209
	v_lshl_add_u64 v[36:37], v[44:45], 2, s[78:79]
	v_lshlrev_b32_e32 v38, 16, v32
	v_and_b32_e32 v39, 0xffff0000, v32
	v_lshlrev_b32_e32 v32, 16, v33
	v_and_b32_e32 v33, 0xffff0000, v33
	v_lshlrev_b32_e32 v40, 16, v34
	v_and_b32_e32 v41, 0xffff0000, v34
	v_lshlrev_b32_e32 v34, 16, v35
	v_and_b32_e32 v35, 0xffff0000, v35
	v_pk_add_f32 v[30:31], v[30:31], v[32:33]
	v_pk_add_f32 v[28:29], v[28:29], v[38:39]
	v_pk_add_f32 v[26:27], v[26:27], v[34:35]
	v_pk_add_f32 v[24:25], v[24:25], v[40:41]
	global_store_dwordx4 v[36:37], v[28:31], off
	global_store_dwordx4 v[36:37], v[24:27], off offset:16
	s_nop 1
	v_mov_b32_e32 v24, v210
	v_mov_b32_e32 v25, v211
	v_mov_b32_e32 v26, v212
	v_mov_b32_e32 v27, v213
	v_add_u32_e32 v28, 0xb0, v136
	v_ashrrev_i32_e32 v29, 31, v28
	v_lshlrev_b64 v[28:29], 10, v[28:29]
	v_lshl_add_u64 v[28:29], v[28:29], 0, v[138:139]
	v_lshl_add_u64 v[30:31], v[28:29], 1, s[10:11]
	v_lshlrev_b32_e32 v32, 16, v24
	v_and_b32_e32 v33, 0xffff0000, v24
	v_lshlrev_b32_e32 v24, 16, v25
	v_and_b32_e32 v25, 0xffff0000, v25
	v_lshlrev_b32_e32 v34, 16, v26
	v_and_b32_e32 v35, 0xffff0000, v26
	v_lshlrev_b32_e32 v26, 16, v27
	v_and_b32_e32 v27, 0xffff0000, v27
	v_pk_add_f32 v[22:23], v[22:23], v[24:25]
	v_pk_add_f32 v[20:21], v[20:21], v[32:33]
	v_pk_add_f32 v[18:19], v[18:19], v[26:27]
	v_pk_add_f32 v[16:17], v[16:17], v[34:35]
	global_store_dwordx4 v[36:37], v[20:23], off offset:512
	global_store_dwordx4 v[36:37], v[16:19], off offset:528
	s_nop 1
	v_mov_b32_e32 v16, v214
	v_mov_b32_e32 v17, v215
	v_mov_b32_e32 v18, v216
	v_mov_b32_e32 v19, v217
	v_lshl_add_u64 v[20:21], v[28:29], 2, s[78:79]
	v_lshlrev_b32_e32 v22, 16, v16
	v_and_b32_e32 v23, 0xffff0000, v16
	v_lshlrev_b32_e32 v16, 16, v17
	v_and_b32_e32 v17, 0xffff0000, v17
	v_lshlrev_b32_e32 v24, 16, v18
	v_and_b32_e32 v25, 0xffff0000, v18
	v_lshlrev_b32_e32 v18, 16, v19
	v_and_b32_e32 v19, 0xffff0000, v19
	v_pk_add_f32 v[14:15], v[14:15], v[16:17]
	v_pk_add_f32 v[12:13], v[12:13], v[22:23]
	v_pk_add_f32 v[10:11], v[10:11], v[18:19]
	v_pk_add_f32 v[8:9], v[8:9], v[24:25]
	global_store_dwordx4 v[20:21], v[12:15], off
	global_store_dwordx4 v[20:21], v[8:11], off offset:16
	s_nop 1
	v_mov_b32_e32 v8, v222
	v_mov_b32_e32 v9, v223
	v_mov_b32_e32 v10, v224
	v_mov_b32_e32 v11, v225
	v_lshlrev_b32_e32 v12, 16, v8
	v_and_b32_e32 v13, 0xffff0000, v8
	v_lshlrev_b32_e32 v8, 16, v9
	v_and_b32_e32 v9, 0xffff0000, v9
	v_lshlrev_b32_e32 v14, 16, v10
	v_and_b32_e32 v15, 0xffff0000, v10
	v_lshlrev_b32_e32 v10, 16, v11
	v_and_b32_e32 v11, 0xffff0000, v11
	v_pk_add_f32 v[6:7], v[6:7], v[8:9]
	v_pk_add_f32 v[4:5], v[4:5], v[12:13]
	v_pk_add_f32 v[2:3], v[2:3], v[10:11]
	v_pk_add_f32 v[0:1], v[0:1], v[14:15]
	global_store_dwordx4 v[20:21], v[4:7], off offset:512
	global_store_dwordx4 v[20:21], v[0:3], off offset:528
	s_cbranch_vccnz .LBB0_1395
	s_andn2_b64 vcc, exec, s[8:9]
	s_cbranch_vccnz .LBB0_1394
	s_barrier
	s_branch .LBB0_1394
